# v36 = v30 with the MT4 k-loop LDS writes front-loaded in ks3 and the next iteration's ks0 fragment reads issued under the last two MFMAs (after the publish barrier)
# baseline (speedup 1.0000x reference)
.LBB0_301:
	s_mul_hi_u32 s0, s55, s25
	s_mul_i32 s1, s0, s20
	s_sub_i32 s1, s55, s1
	s_add_i32 s8, s0, 1
	s_sub_i32 s12, s1, s20
	s_cmp_ge_u32 s1, s20
	s_cselect_b32 s0, s8, s0
	s_cselect_b32 s1, s12, s1
	s_add_i32 s8, s0, 1
	s_cmp_ge_u32 s1, s20
	s_cselect_b32 s0, s8, s0
	s_add_i32 s1, s0, s23
	s_mul_i32 s0, s0, s20
	s_sub_i32 s0, s55, s0
	s_add_i32 s0, s0, s19
	s_lshl_b32 s12, s1, 8
	s_lshl_b32 s8, s0, 7
	s_mov_b64 s[0:1], s[30:31]
	v_mov_b32_e32 v0, v177
	s_mov_b32 s13, s9
	v_mbcnt_lo_u32_b32 v0, -1, v0
	v_mbcnt_hi_u32_b32 v0, -1, v0
	v_add_u32_e32 v182, s33, v0
	s_lshl_b64 s[16:17], s[12:13], 11
	v_ashrrev_i32_e32 v0, 3, v182
	v_lshlrev_b32_e32 v1, 3, v182
	s_add_u32 s56, s14, s16
	v_and_b32_e32 v6, 56, v1
	v_lshlrev_b32_e32 v1, 11, v0
	s_addc_u32 s57, s15, s17
	v_lshl_or_b32 v176, v6, 1, v1
	v_mul_lo_u32 v7, v0, s21
	v_lshl_add_u64 v[0:1], s[56:57], 0, v[176:177]
	v_add_co_u32_e32 v2, vcc, s26, v0
	s_lshl_b64 s[58:59], s[8:9], 11
	s_nop 0
	v_addc_co_u32_e32 v3, vcc, 0, v1, vcc
	v_add_co_u32_e32 v4, vcc, s27, v0
	s_add_u32 s58, s30, s58
	s_nop 0
	v_addc_co_u32_e32 v5, vcc, 0, v1, vcc
	global_load_dwordx4 v[128:131], v[2:3], off
	global_load_dwordx4 v[132:135], v[4:5], off
	v_add_co_u32_e32 v2, vcc, s34, v0
	s_addc_u32 s59, s31, s59
	s_nop 0
	v_addc_co_u32_e32 v3, vcc, 0, v1, vcc
	v_add_co_u32_e32 v4, vcc, s35, v0
	v_lshl_add_u64 v[178:179], s[58:59], 0, v[176:177]
	s_nop 0
	v_addc_co_u32_e32 v5, vcc, 0, v1, vcc
	global_load_dwordx4 v[136:139], v[2:3], off
	global_load_dwordx4 v[144:147], v[4:5], off
	v_add_co_u32_e32 v2, vcc, s36, v0
	v_bfe_u32 v185, v182, 6, 1
	s_nop 0
	v_addc_co_u32_e32 v3, vcc, 0, v1, vcc
	v_add_co_u32_e32 v4, vcc, s37, v0
	v_and_b32_e32 v184, 31, v182
	s_nop 0
	v_addc_co_u32_e32 v5, vcc, 0, v1, vcc
	v_add_co_u32_e32 v0, vcc, s38, v0
	global_load_dwordx4 v[148:151], v[2:3], off
	global_load_dwordx4 v[152:155], v[4:5], off
	v_addc_co_u32_e32 v1, vcc, 0, v1, vcc
	v_add_co_u32_e32 v2, vcc, s26, v178
	global_load_dwordx4 v[164:167], v176, s[56:57]
	global_load_dwordx4 v[140:143], v176, s[58:59]
	v_addc_co_u32_e32 v3, vcc, 0, v179, vcc
	global_load_dwordx4 v[156:159], v[0:1], off
	global_load_dwordx4 v[160:163], v[2:3], off
	v_add_co_u32_e32 v0, vcc, s27, v178
	v_bfe_u32 v186, v182, 5, 1
	s_nop 0
	v_addc_co_u32_e32 v1, vcc, 0, v179, vcc
	v_add_co_u32_e32 v2, vcc, s34, v178
	s_add_u32 s16, s30, s16
	s_nop 0
	v_addc_co_u32_e32 v3, vcc, 0, v179, vcc
	global_load_dwordx4 v[168:171], v[0:1], off
	global_load_dwordx4 v[172:175], v[2:3], off
	v_and_b32_e32 v0, 0xfffff9f, v182
	v_lshl_or_b32 v2, v185, 6, v184
	v_mul_lo_u32 v3, v0, s39
	v_or_b32_e32 v0, 0x60, v182
	v_lshlrev_b32_e32 v1, 4, v186
	v_mul_lo_u32 v4, v0, s39
	v_mul_u32_u24_e32 v2, 0x90, v2
	s_addc_u32 s17, s31, s17
	v_mov_b32_e32 v0, 0
	v_add_lshl_u32 v189, v7, v6, 1
	v_lshl_add_u64 v[180:181], s[16:17], 0, v[176:177]
	s_mov_b64 s[16:17], 0
	v_add_u32_e32 v188, v1, v3
	v_add_u32_e32 v187, v1, v4
	v_add_u32_e32 v176, v1, v2
	v_mov_b32_e32 v1, v0
	v_mov_b32_e32 v2, v0
	v_mov_b32_e32 v3, v0
	v_mov_b32_e32 v4, v0
	v_mov_b32_e32 v5, v0
	v_mov_b32_e32 v6, v0
	v_mov_b32_e32 v7, v0
	v_mov_b32_e32 v8, v0
	v_mov_b32_e32 v9, v0
	v_mov_b32_e32 v10, v0
	v_mov_b32_e32 v11, v0
	v_mov_b32_e32 v12, v0
	v_mov_b32_e32 v13, v0
	v_mov_b32_e32 v14, v0
	v_mov_b32_e32 v15, v0
	v_mov_b32_e32 v16, v0
	v_mov_b32_e32 v17, v0
	v_mov_b32_e32 v18, v0
	v_mov_b32_e32 v19, v0
	v_mov_b32_e32 v20, v0
	v_mov_b32_e32 v21, v0
	v_mov_b32_e32 v22, v0
	v_mov_b32_e32 v23, v0
	v_mov_b32_e32 v24, v0
	v_mov_b32_e32 v25, v0
	v_mov_b32_e32 v26, v0
	v_mov_b32_e32 v27, v0
	v_mov_b32_e32 v28, v0
	v_mov_b32_e32 v29, v0
	v_mov_b32_e32 v30, v0
	v_mov_b32_e32 v31, v0
	v_mov_b32_e32 v32, v0
	v_mov_b32_e32 v33, v0
	v_mov_b32_e32 v34, v0
	v_mov_b32_e32 v35, v0
	v_mov_b32_e32 v36, v0
	v_mov_b32_e32 v37, v0
	v_mov_b32_e32 v38, v0
	v_mov_b32_e32 v39, v0
	v_mov_b32_e32 v40, v0
	v_mov_b32_e32 v41, v0
	v_mov_b32_e32 v42, v0
	v_mov_b32_e32 v43, v0
	v_mov_b32_e32 v44, v0
	v_mov_b32_e32 v45, v0
	v_mov_b32_e32 v46, v0
	v_mov_b32_e32 v47, v0
	v_mov_b32_e32 v48, v0
	v_mov_b32_e32 v49, v0
	v_mov_b32_e32 v50, v0
	v_mov_b32_e32 v51, v0
	v_mov_b32_e32 v52, v0
	v_mov_b32_e32 v53, v0
	v_mov_b32_e32 v54, v0
	v_mov_b32_e32 v55, v0
	v_mov_b32_e32 v56, v0
	v_mov_b32_e32 v57, v0
	v_mov_b32_e32 v58, v0
	v_mov_b32_e32 v59, v0
	v_mov_b32_e32 v60, v0
	v_mov_b32_e32 v61, v0
	v_mov_b32_e32 v62, v0
	v_mov_b32_e32 v63, v0
	v_mov_b32_e32 v64, v0
	v_mov_b32_e32 v65, v0
	v_mov_b32_e32 v66, v0
	v_mov_b32_e32 v67, v0
	v_mov_b32_e32 v68, v0
	v_mov_b32_e32 v69, v0
	v_mov_b32_e32 v70, v0
	v_mov_b32_e32 v71, v0
	v_mov_b32_e32 v72, v0
	v_mov_b32_e32 v73, v0
	v_mov_b32_e32 v74, v0
	v_mov_b32_e32 v75, v0
	v_mov_b32_e32 v76, v0
	v_mov_b32_e32 v77, v0
	v_mov_b32_e32 v78, v0
	v_mov_b32_e32 v79, v0
	v_mov_b32_e32 v80, v0
	v_mov_b32_e32 v81, v0
	v_mov_b32_e32 v82, v0
	v_mov_b32_e32 v83, v0
	v_mov_b32_e32 v84, v0
	v_mov_b32_e32 v85, v0
	v_mov_b32_e32 v86, v0
	v_mov_b32_e32 v87, v0
	v_mov_b32_e32 v88, v0
	v_mov_b32_e32 v89, v0
	v_mov_b32_e32 v90, v0
	v_mov_b32_e32 v91, v0
	v_mov_b32_e32 v92, v0
	v_mov_b32_e32 v93, v0
	v_mov_b32_e32 v94, v0
	v_mov_b32_e32 v95, v0
	v_mov_b32_e32 v96, v0
	v_mov_b32_e32 v97, v0
	v_mov_b32_e32 v98, v0
	v_mov_b32_e32 v99, v0
	v_mov_b32_e32 v100, v0
	v_mov_b32_e32 v101, v0
	v_mov_b32_e32 v102, v0
	v_mov_b32_e32 v103, v0
	v_mov_b32_e32 v104, v0
	v_mov_b32_e32 v105, v0
	v_mov_b32_e32 v106, v0
	v_mov_b32_e32 v107, v0
	v_mov_b32_e32 v108, v0
	v_mov_b32_e32 v109, v0
	v_mov_b32_e32 v110, v0
	v_mov_b32_e32 v111, v0
	v_mov_b32_e32 v112, v0
	v_mov_b32_e32 v113, v0
	v_mov_b32_e32 v114, v0
	v_mov_b32_e32 v115, v0
	v_mov_b32_e32 v116, v0
	v_mov_b32_e32 v117, v0
	v_mov_b32_e32 v118, v0
	v_mov_b32_e32 v119, v0
	v_mov_b32_e32 v120, v0
	v_mov_b32_e32 v121, v0
	v_mov_b32_e32 v122, v0
	v_mov_b32_e32 v123, v0
	v_mov_b32_e32 v124, v0
	v_mov_b32_e32 v125, v0
	v_mov_b32_e32 v126, v0
	v_mov_b32_e32 v127, v0
	v_readfirstlane_b32 s40, v180
	v_readfirstlane_b32 s41, v181
	v_readfirstlane_b32 s42, v178
	v_readfirstlane_b32 s43, v179
	v_lshrrev_b32_e32 v198, 3, v182
	v_and_b32_e32 v199, 7, v182
	v_lshlrev_b32_e32 v198, 11, v198
	v_lshl_or_b32 v190, v199, 4, v198
	s_lshl_b32 s44, s33, 8
	s_sub_u32 s40, s40, s44
	s_subb_u32 s41, s41, 0
	s_sub_u32 s42, s42, s44
	s_subb_u32 s43, s43, 0
	s_add_u32 s40, s40, 0x2957980
	s_addc_u32 s41, s41, 0
	s_add_u32 s42, s42, 0x80
	s_addc_u32 s43, s43, 0
	v_add_u32_e32 v191, 0x10000, v190
	v_add_u32_e32 v192, 0x20000, v190
	v_add_u32_e32 v193, 0x30000, v190
	v_add_u32_e32 v194, 0x40000, v190
	v_add_u32_e32 v195, 0x50000, v190
	v_add_u32_e32 v196, 0x60000, v190
	v_add_u32_e32 v197, 0x70000, v190
	s_waitcnt lgkmcnt(0)
	s_barrier
	s_waitcnt vmcnt(0)
	ds_write_b128 v189, v[164:167]
	ds_write_b128 v189, v[128:131] offset:4608
	ds_write_b128 v189, v[132:135] offset:9216
	ds_write_b128 v189, v[136:139] offset:13824
	ds_write_b128 v189, v[144:147] offset:18432
	ds_write_b128 v189, v[148:151] offset:23040
	ds_write_b128 v189, v[152:155] offset:27648
	ds_write_b128 v189, v[156:159] offset:32256
	ds_write_b128 v189, v[140:143] offset:36864
	ds_write_b128 v189, v[160:163] offset:41472
	ds_write_b128 v189, v[168:171] offset:46080
	ds_write_b128 v189, v[172:175] offset:50688
	global_load_dwordx4 v[164:167], v190, s[40:41]
	global_load_dwordx4 v[128:131], v191, s[40:41]
	global_load_dwordx4 v[132:135], v192, s[40:41]
	global_load_dwordx4 v[136:139], v193, s[40:41]
	global_load_dwordx4 v[144:147], v194, s[40:41]
	global_load_dwordx4 v[148:151], v195, s[40:41]
	s_waitcnt lgkmcnt(0)
	s_barrier
	ds_read_b128 v[216:219], v176 offset:36864
	ds_read_b128 v[200:203], v188
	ds_read_b128 v[220:223], v176 offset:41472
	ds_read_b128 v[204:207], v188 offset:4608
	ds_read_b128 v[208:211], v188 offset:9216
	ds_read_b128 v[212:215], v187
.LBB0_302:
	s_waitcnt lgkmcnt(4)
	v_mfma_f32_32x32x16_bf16 v[112:127], v[200:203], v[216:219], v[112:127]
	ds_read_b128 v[240:243], v176 offset:36896
	global_load_dwordx4 v[140:143], v190, s[42:43]
	s_waitcnt lgkmcnt(4)
	v_mfma_f32_32x32x16_bf16 v[96:111], v[200:203], v[220:223], v[96:111]
	ds_read_b128 v[224:227], v188 offset:32
	global_load_dwordx4 v[160:163], v191, s[42:43]
	s_waitcnt lgkmcnt(4)
	v_mfma_f32_32x32x16_bf16 v[80:95], v[204:207], v[216:219], v[80:95]
	ds_read_b128 v[244:247], v176 offset:41504
	global_load_dwordx4 v[168:171], v192, s[42:43]
	s_waitcnt lgkmcnt(5)
	v_mfma_f32_32x32x16_bf16 v[64:79], v[204:207], v[220:223], v[64:79]
	ds_read_b128 v[228:231], v188 offset:4640
	global_load_dwordx4 v[172:175], v193, s[42:43]
	s_waitcnt lgkmcnt(5)
	v_mfma_f32_32x32x16_bf16 v[48:63], v[208:211], v[216:219], v[48:63]
	ds_read_b128 v[232:235], v188 offset:9248
	global_load_dwordx4 v[152:155], v196, s[40:41]
	s_waitcnt lgkmcnt(6)
	v_mfma_f32_32x32x16_bf16 v[32:47], v[208:211], v[220:223], v[32:47]
	ds_read_b128 v[236:239], v187 offset:32
	global_load_dwordx4 v[156:159], v197, s[40:41]
	s_add_u32 s40, s40, 0x80
	s_addc_u32 s41, s41, 0
	s_add_u32 s42, s42, 0x80
	s_addc_u32 s43, s43, 0
	s_add_u32 s16, s16, 0x80
	s_waitcnt lgkmcnt(6)
	v_mfma_f32_32x32x16_bf16 v[16:31], v[212:215], v[216:219], v[16:31]
	s_waitcnt lgkmcnt(6)
	v_mfma_f32_32x32x16_bf16 v[0:15], v[212:215], v[220:223], v[0:15]
	s_waitcnt lgkmcnt(4)
	v_mfma_f32_32x32x16_bf16 v[112:127], v[224:227], v[240:243], v[112:127]
	ds_read_b128 v[200:203], v188 offset:64
	s_waitcnt lgkmcnt(4)
	v_mfma_f32_32x32x16_bf16 v[96:111], v[224:227], v[244:247], v[96:111]
	ds_read_b128 v[204:207], v188 offset:4672
	s_waitcnt lgkmcnt(4)
	v_mfma_f32_32x32x16_bf16 v[80:95], v[228:231], v[240:243], v[80:95]
	ds_read_b128 v[208:211], v188 offset:9280
	s_waitcnt lgkmcnt(5)
	v_mfma_f32_32x32x16_bf16 v[64:79], v[228:231], v[244:247], v[64:79]
	ds_read_b128 v[212:215], v187 offset:64
	s_waitcnt lgkmcnt(5)
	v_mfma_f32_32x32x16_bf16 v[48:63], v[232:235], v[240:243], v[48:63]
	ds_read_b128 v[216:219], v176 offset:36928
	s_waitcnt lgkmcnt(6)
	v_mfma_f32_32x32x16_bf16 v[32:47], v[232:235], v[244:247], v[32:47]
	ds_read_b128 v[220:223], v176 offset:41536
	s_waitcnt lgkmcnt(6)
	v_mfma_f32_32x32x16_bf16 v[16:31], v[236:239], v[240:243], v[16:31]
	s_waitcnt lgkmcnt(6)
	v_mfma_f32_32x32x16_bf16 v[0:15], v[236:239], v[244:247], v[0:15]
	s_waitcnt lgkmcnt(1)
	v_mfma_f32_32x32x16_bf16 v[112:127], v[200:203], v[216:219], v[112:127]
	ds_read_b128 v[224:227], v188 offset:96
	s_waitcnt lgkmcnt(1)
	v_mfma_f32_32x32x16_bf16 v[96:111], v[200:203], v[220:223], v[96:111]
	ds_read_b128 v[228:231], v188 offset:4704
	s_waitcnt lgkmcnt(3)
	v_mfma_f32_32x32x16_bf16 v[80:95], v[204:207], v[216:219], v[80:95]
	ds_read_b128 v[232:235], v188 offset:9312
	s_waitcnt lgkmcnt(3)
	v_mfma_f32_32x32x16_bf16 v[64:79], v[204:207], v[220:223], v[64:79]
	ds_read_b128 v[236:239], v187 offset:96
	s_waitcnt lgkmcnt(5)
	v_mfma_f32_32x32x16_bf16 v[48:63], v[208:211], v[216:219], v[48:63]
	ds_read_b128 v[240:243], v176 offset:36960
	s_waitcnt lgkmcnt(5)
	v_mfma_f32_32x32x16_bf16 v[32:47], v[208:211], v[220:223], v[32:47]
	ds_read_b128 v[244:247], v176 offset:41568
	s_waitcnt lgkmcnt(7)
	v_mfma_f32_32x32x16_bf16 v[16:31], v[212:215], v[216:219], v[16:31]
	s_waitcnt lgkmcnt(6)
	v_mfma_f32_32x32x16_bf16 v[0:15], v[212:215], v[220:223], v[0:15]
	s_waitcnt lgkmcnt(0)
	s_barrier
	s_waitcnt vmcnt(6)
	s_waitcnt lgkmcnt(1)
	v_mfma_f32_32x32x16_bf16 v[112:127], v[224:227], v[240:243], v[112:127]
	ds_write_b128 v189, v[164:167]
	ds_write_b128 v189, v[128:131] offset:4608
	s_waitcnt lgkmcnt(2)
	v_mfma_f32_32x32x16_bf16 v[96:111], v[224:227], v[244:247], v[96:111]
	ds_write_b128 v189, v[132:135] offset:9216
	ds_write_b128 v189, v[136:139] offset:13824
	global_load_dwordx4 v[164:167], v190, s[40:41]
	s_waitcnt lgkmcnt(5)
	v_mfma_f32_32x32x16_bf16 v[80:95], v[228:231], v[240:243], v[80:95]
	ds_write_b128 v189, v[144:147] offset:18432
	ds_write_b128 v189, v[148:151] offset:23040
	global_load_dwordx4 v[128:131], v191, s[40:41]
	s_waitcnt lgkmcnt(6)
	v_mfma_f32_32x32x16_bf16 v[64:79], v[228:231], v[244:247], v[64:79]
	s_waitcnt vmcnt(2)
	ds_write_b128 v189, v[152:155] offset:27648
	ds_write_b128 v189, v[156:159] offset:32256
	global_load_dwordx4 v[132:135], v192, s[40:41]
	s_waitcnt lgkmcnt(9)
	v_mfma_f32_32x32x16_bf16 v[48:63], v[232:235], v[240:243], v[48:63]
	ds_write_b128 v189, v[140:143] offset:36864
	ds_write_b128 v189, v[160:163] offset:41472
	global_load_dwordx4 v[136:139], v193, s[40:41]
	s_waitcnt lgkmcnt(10)
	v_mfma_f32_32x32x16_bf16 v[32:47], v[232:235], v[244:247], v[32:47]
	ds_write_b128 v189, v[168:171] offset:46080
	ds_write_b128 v189, v[172:175] offset:50688
	global_load_dwordx4 v[144:147], v194, s[40:41]
	global_load_dwordx4 v[148:151], v195, s[40:41]
	s_waitcnt lgkmcnt(0)
	s_barrier
	ds_read_b128 v[216:219], v176 offset:36864
	ds_read_b128 v[200:203], v188
	ds_read_b128 v[220:223], v176 offset:41472
	ds_read_b128 v[204:207], v188 offset:4608
	ds_read_b128 v[208:211], v188 offset:9216
	ds_read_b128 v[212:215], v187
	s_waitcnt lgkmcnt(15)
	v_mfma_f32_32x32x16_bf16 v[16:31], v[236:239], v[240:243], v[16:31]
	s_waitcnt lgkmcnt(15)
	v_mfma_f32_32x32x16_bf16 v[0:15], v[236:239], v[244:247], v[0:15]
	s_cmpk_lg_i32 s16, 0x780
	s_cbranch_scc1 .LBB0_302
	s_waitcnt lgkmcnt(4)
	v_mfma_f32_32x32x16_bf16 v[112:127], v[200:203], v[216:219], v[112:127]
	ds_read_b128 v[240:243], v176 offset:36896
	s_waitcnt lgkmcnt(4)
	v_mfma_f32_32x32x16_bf16 v[96:111], v[200:203], v[220:223], v[96:111]
	ds_read_b128 v[224:227], v188 offset:32
	s_waitcnt lgkmcnt(4)
	v_mfma_f32_32x32x16_bf16 v[80:95], v[204:207], v[216:219], v[80:95]
	ds_read_b128 v[244:247], v176 offset:41504
	s_waitcnt lgkmcnt(5)
	v_mfma_f32_32x32x16_bf16 v[64:79], v[204:207], v[220:223], v[64:79]
	ds_read_b128 v[228:231], v188 offset:4640
	s_waitcnt lgkmcnt(5)
	v_mfma_f32_32x32x16_bf16 v[48:63], v[208:211], v[216:219], v[48:63]
	ds_read_b128 v[232:235], v188 offset:9248
	s_waitcnt lgkmcnt(6)
	v_mfma_f32_32x32x16_bf16 v[32:47], v[208:211], v[220:223], v[32:47]
	ds_read_b128 v[236:239], v187 offset:32
	s_waitcnt lgkmcnt(6)
	v_mfma_f32_32x32x16_bf16 v[16:31], v[212:215], v[216:219], v[16:31]
	s_waitcnt lgkmcnt(6)
	v_mfma_f32_32x32x16_bf16 v[0:15], v[212:215], v[220:223], v[0:15]
	s_waitcnt lgkmcnt(4)
	v_mfma_f32_32x32x16_bf16 v[112:127], v[224:227], v[240:243], v[112:127]
	ds_read_b128 v[200:203], v188 offset:64
	s_waitcnt lgkmcnt(4)
	v_mfma_f32_32x32x16_bf16 v[96:111], v[224:227], v[244:247], v[96:111]
	ds_read_b128 v[204:207], v188 offset:4672
	s_waitcnt lgkmcnt(4)
	v_mfma_f32_32x32x16_bf16 v[80:95], v[228:231], v[240:243], v[80:95]
	ds_read_b128 v[208:211], v188 offset:9280
	s_waitcnt lgkmcnt(5)
	v_mfma_f32_32x32x16_bf16 v[64:79], v[228:231], v[244:247], v[64:79]
	ds_read_b128 v[212:215], v187 offset:64
	s_waitcnt lgkmcnt(5)
	v_mfma_f32_32x32x16_bf16 v[48:63], v[232:235], v[240:243], v[48:63]
	ds_read_b128 v[216:219], v176 offset:36928
	s_waitcnt lgkmcnt(6)
	v_mfma_f32_32x32x16_bf16 v[32:47], v[232:235], v[244:247], v[32:47]
	ds_read_b128 v[220:223], v176 offset:41536
	s_waitcnt lgkmcnt(6)
	v_mfma_f32_32x32x16_bf16 v[16:31], v[236:239], v[240:243], v[16:31]
	s_waitcnt lgkmcnt(6)
	v_mfma_f32_32x32x16_bf16 v[0:15], v[236:239], v[244:247], v[0:15]
	s_waitcnt lgkmcnt(1)
	v_mfma_f32_32x32x16_bf16 v[112:127], v[200:203], v[216:219], v[112:127]
	ds_read_b128 v[224:227], v188 offset:96
	s_waitcnt lgkmcnt(1)
	v_mfma_f32_32x32x16_bf16 v[96:111], v[200:203], v[220:223], v[96:111]
	ds_read_b128 v[228:231], v188 offset:4704
	s_waitcnt lgkmcnt(3)
	v_mfma_f32_32x32x16_bf16 v[80:95], v[204:207], v[216:219], v[80:95]
	ds_read_b128 v[232:235], v188 offset:9312
	s_waitcnt lgkmcnt(3)
	v_mfma_f32_32x32x16_bf16 v[64:79], v[204:207], v[220:223], v[64:79]
	ds_read_b128 v[236:239], v187 offset:96
	s_waitcnt lgkmcnt(5)
	v_mfma_f32_32x32x16_bf16 v[48:63], v[208:211], v[216:219], v[48:63]
	ds_read_b128 v[240:243], v176 offset:36960
	s_waitcnt lgkmcnt(5)
	v_mfma_f32_32x32x16_bf16 v[32:47], v[208:211], v[220:223], v[32:47]
	ds_read_b128 v[244:247], v176 offset:41568
	s_waitcnt lgkmcnt(7)
	v_mfma_f32_32x32x16_bf16 v[16:31], v[212:215], v[216:219], v[16:31]
	s_waitcnt lgkmcnt(6)
	v_mfma_f32_32x32x16_bf16 v[0:15], v[212:215], v[220:223], v[0:15]
	s_waitcnt lgkmcnt(1)
	v_mfma_f32_32x32x16_bf16 v[112:127], v[224:227], v[240:243], v[112:127]
	s_waitcnt lgkmcnt(0)
	v_mfma_f32_32x32x16_bf16 v[96:111], v[224:227], v[244:247], v[96:111]
	s_waitcnt lgkmcnt(1)
	v_mfma_f32_32x32x16_bf16 v[80:95], v[228:231], v[240:243], v[80:95]
	s_waitcnt lgkmcnt(0)
	v_mfma_f32_32x32x16_bf16 v[64:79], v[228:231], v[244:247], v[64:79]
	s_waitcnt lgkmcnt(1)
	v_mfma_f32_32x32x16_bf16 v[48:63], v[232:235], v[240:243], v[48:63]
	s_waitcnt lgkmcnt(0)
	v_mfma_f32_32x32x16_bf16 v[32:47], v[232:235], v[244:247], v[32:47]
	s_waitcnt lgkmcnt(1)
	v_mfma_f32_32x32x16_bf16 v[16:31], v[236:239], v[240:243], v[16:31]
	s_waitcnt lgkmcnt(0)
	v_mfma_f32_32x32x16_bf16 v[0:15], v[236:239], v[244:247], v[0:15]
	s_waitcnt vmcnt(0)
	s_mul_i32 s44, s12, 0x1240
	s_add_u32 s40, s30, s44
	s_addc_u32 s41, s31, 0
	s_lshl_b32 s44, s8, 1
	s_add_u32 s40, s40, s44
	s_addc_u32 s41, s41, 0
	s_add_u32 s40, s40, 0x7157900
	s_addc_u32 s41, s41, 0
	v_and_b32_e32 v131, 15, v182
	v_lshrrev_b32_e32 v172, 4, v182
	v_lshl_add_u32 v130, v131, 3, s8
	s_movk_i32 s44, 0x920
	v_cmp_gt_u32_e64 s[42:43], s44, v130
	v_mul_u32_u24_e32 v164, 0x1240, v172
	v_lshl_add_u32 v164, v131, 4, v164
	v_add_u32_e32 v165, 0x12400, v164
	v_add_u32_e32 v166, 0x24800, v164
	v_add_u32_e32 v167, 0x36c00, v164
	v_add_u32_e32 v168, 0x92000, v164
	v_add_u32_e32 v169, 0xa4400, v164
	v_add_u32_e32 v170, 0xb6800, v164
	v_add_u32_e32 v171, 0xc8c00, v164
	v_mul_u32_u24_e32 v129, 0x110, v172
	v_lshl_add_u32 v129, v131, 4, v129
	v_lshrrev_b32_e32 v131, 7, v182
	v_bfe_u32 v172, v182, 5, 1
	v_lshlrev_b32_e32 v131, 6, v131
	v_lshl_or_b32 v131, v172, 2, v131
	v_mul_u32_u24_e32 v131, 136, v131
	v_and_b32_e32 v172, 0x5f, v182
	v_add_lshl_u32 v128, v131, v172, 1
	s_barrier
	v_cvt_pk_bf16_f32 v112, v112, v113
	v_cvt_pk_bf16_f32 v114, v114, v115
	v_cvt_pk_bf16_f32 v116, v116, v117
	v_cvt_pk_bf16_f32 v118, v118, v119
	v_cvt_pk_bf16_f32 v120, v120, v121
	v_cvt_pk_bf16_f32 v122, v122, v123
	v_cvt_pk_bf16_f32 v124, v124, v125
	v_cvt_pk_bf16_f32 v126, v126, v127
	v_cvt_pk_bf16_f32 v96, v96, v97
	v_cvt_pk_bf16_f32 v98, v98, v99
	v_cvt_pk_bf16_f32 v100, v100, v101
	v_cvt_pk_bf16_f32 v102, v102, v103
	v_cvt_pk_bf16_f32 v104, v104, v105
	v_cvt_pk_bf16_f32 v106, v106, v107
	v_cvt_pk_bf16_f32 v108, v108, v109
	v_cvt_pk_bf16_f32 v110, v110, v111
	v_cvt_pk_bf16_f32 v80, v80, v81
	v_cvt_pk_bf16_f32 v82, v82, v83
	v_cvt_pk_bf16_f32 v84, v84, v85
	v_cvt_pk_bf16_f32 v86, v86, v87
	v_cvt_pk_bf16_f32 v88, v88, v89
	v_cvt_pk_bf16_f32 v90, v90, v91
	v_cvt_pk_bf16_f32 v92, v92, v93
	v_cvt_pk_bf16_f32 v94, v94, v95
	v_cvt_pk_bf16_f32 v64, v64, v65
	v_cvt_pk_bf16_f32 v66, v66, v67
	v_cvt_pk_bf16_f32 v68, v68, v69
	v_cvt_pk_bf16_f32 v70, v70, v71
	v_cvt_pk_bf16_f32 v72, v72, v73
	v_cvt_pk_bf16_f32 v74, v74, v75
	v_cvt_pk_bf16_f32 v76, v76, v77
	v_cvt_pk_bf16_f32 v78, v78, v79
	ds_write_b16 v128, v112
	ds_write_b16_d16_hi v128, v112 offset:272
	ds_write_b16 v128, v114 offset:544
	ds_write_b16_d16_hi v128, v114 offset:816
	ds_write_b16 v128, v116 offset:2176
	ds_write_b16_d16_hi v128, v116 offset:2448
	ds_write_b16 v128, v118 offset:2720
	ds_write_b16_d16_hi v128, v118 offset:2992
	ds_write_b16 v128, v120 offset:4352
	ds_write_b16_d16_hi v128, v120 offset:4624
	ds_write_b16 v128, v122 offset:4896
	ds_write_b16_d16_hi v128, v122 offset:5168
	ds_write_b16 v128, v124 offset:6528
	ds_write_b16_d16_hi v128, v124 offset:6800
	ds_write_b16 v128, v126 offset:7072
	ds_write_b16_d16_hi v128, v126 offset:7344
	ds_write_b16 v128, v96 offset:64
	ds_write_b16_d16_hi v128, v96 offset:336
	ds_write_b16 v128, v98 offset:608
	ds_write_b16_d16_hi v128, v98 offset:880
	ds_write_b16 v128, v100 offset:2240
	ds_write_b16_d16_hi v128, v100 offset:2512
	ds_write_b16 v128, v102 offset:2784
	ds_write_b16_d16_hi v128, v102 offset:3056
	ds_write_b16 v128, v104 offset:4416
	ds_write_b16_d16_hi v128, v104 offset:4688
	ds_write_b16 v128, v106 offset:4960
	ds_write_b16_d16_hi v128, v106 offset:5232
	ds_write_b16 v128, v108 offset:6592
	ds_write_b16_d16_hi v128, v108 offset:6864
	ds_write_b16 v128, v110 offset:7136
	ds_write_b16_d16_hi v128, v110 offset:7408
	ds_write_b16 v128, v80 offset:8704
	ds_write_b16_d16_hi v128, v80 offset:8976
	ds_write_b16 v128, v82 offset:9248
	ds_write_b16_d16_hi v128, v82 offset:9520
	ds_write_b16 v128, v84 offset:10880
	ds_write_b16_d16_hi v128, v84 offset:11152
	ds_write_b16 v128, v86 offset:11424
	ds_write_b16_d16_hi v128, v86 offset:11696
	ds_write_b16 v128, v88 offset:13056
	ds_write_b16_d16_hi v128, v88 offset:13328
	ds_write_b16 v128, v90 offset:13600
	ds_write_b16_d16_hi v128, v90 offset:13872
	ds_write_b16 v128, v92 offset:15232
	ds_write_b16_d16_hi v128, v92 offset:15504
	ds_write_b16 v128, v94 offset:15776
	ds_write_b16_d16_hi v128, v94 offset:16048
	ds_write_b16 v128, v64 offset:8768
	ds_write_b16_d16_hi v128, v64 offset:9040
	ds_write_b16 v128, v66 offset:9312
	ds_write_b16_d16_hi v128, v66 offset:9584
	ds_write_b16 v128, v68 offset:10944
	ds_write_b16_d16_hi v128, v68 offset:11216
	ds_write_b16 v128, v70 offset:11488
	ds_write_b16_d16_hi v128, v70 offset:11760
	ds_write_b16 v128, v72 offset:13120
	ds_write_b16_d16_hi v128, v72 offset:13392
	ds_write_b16 v128, v74 offset:13664
	ds_write_b16_d16_hi v128, v74 offset:13936
	ds_write_b16 v128, v76 offset:15296
	ds_write_b16_d16_hi v128, v76 offset:15568
	ds_write_b16 v128, v78 offset:15840
	ds_write_b16_d16_hi v128, v78 offset:16112
	s_waitcnt lgkmcnt(0)
	s_barrier
	ds_read_b128 v[132:135], v129
	ds_read_b128 v[136:139], v129 offset:4352
	ds_read_b128 v[140:143], v129 offset:8704
	ds_read_b128 v[144:147], v129 offset:13056
	ds_read_b128 v[148:151], v129 offset:17408
	ds_read_b128 v[152:155], v129 offset:21760
	ds_read_b128 v[156:159], v129 offset:26112
	ds_read_b128 v[160:163], v129 offset:30464
	v_cvt_pk_bf16_f32 v48, v48, v49
	v_cvt_pk_bf16_f32 v50, v50, v51
	v_cvt_pk_bf16_f32 v52, v52, v53
	v_cvt_pk_bf16_f32 v54, v54, v55
	v_cvt_pk_bf16_f32 v56, v56, v57
	v_cvt_pk_bf16_f32 v58, v58, v59
	v_cvt_pk_bf16_f32 v60, v60, v61
	v_cvt_pk_bf16_f32 v62, v62, v63
	v_cvt_pk_bf16_f32 v32, v32, v33
	v_cvt_pk_bf16_f32 v34, v34, v35
	v_cvt_pk_bf16_f32 v36, v36, v37
	v_cvt_pk_bf16_f32 v38, v38, v39
	v_cvt_pk_bf16_f32 v40, v40, v41
	v_cvt_pk_bf16_f32 v42, v42, v43
	v_cvt_pk_bf16_f32 v44, v44, v45
	v_cvt_pk_bf16_f32 v46, v46, v47
	v_cvt_pk_bf16_f32 v16, v16, v17
	v_cvt_pk_bf16_f32 v18, v18, v19
	v_cvt_pk_bf16_f32 v20, v20, v21
	v_cvt_pk_bf16_f32 v22, v22, v23
	v_cvt_pk_bf16_f32 v24, v24, v25
	v_cvt_pk_bf16_f32 v26, v26, v27
	v_cvt_pk_bf16_f32 v28, v28, v29
	v_cvt_pk_bf16_f32 v30, v30, v31
	v_cvt_pk_bf16_f32 v0, v0, v1
	v_cvt_pk_bf16_f32 v2, v2, v3
	v_cvt_pk_bf16_f32 v4, v4, v5
	v_cvt_pk_bf16_f32 v6, v6, v7
	v_cvt_pk_bf16_f32 v8, v8, v9
	v_cvt_pk_bf16_f32 v10, v10, v11
	v_cvt_pk_bf16_f32 v12, v12, v13
	v_cvt_pk_bf16_f32 v14, v14, v15
	s_and_saveexec_b64 s[46:47], s[42:43]
	s_waitcnt lgkmcnt(7)
	global_store_dwordx4 v164, v[132:135], s[40:41]
	s_waitcnt lgkmcnt(6)
	global_store_dwordx4 v165, v[136:139], s[40:41]
	s_waitcnt lgkmcnt(5)
	global_store_dwordx4 v166, v[140:143], s[40:41]
	s_waitcnt lgkmcnt(4)
	global_store_dwordx4 v167, v[144:147], s[40:41]
	s_waitcnt lgkmcnt(3)
	global_store_dwordx4 v168, v[148:151], s[40:41]
	s_waitcnt lgkmcnt(2)
	global_store_dwordx4 v169, v[152:155], s[40:41]
	s_waitcnt lgkmcnt(1)
	global_store_dwordx4 v170, v[156:159], s[40:41]
	s_waitcnt lgkmcnt(0)
	global_store_dwordx4 v171, v[160:163], s[40:41]
	s_or_b64 exec, exec, s[46:47]
	s_barrier
	ds_write_b16 v128, v48
	ds_write_b16_d16_hi v128, v48 offset:272
	ds_write_b16 v128, v50 offset:544
	ds_write_b16_d16_hi v128, v50 offset:816
	ds_write_b16 v128, v52 offset:2176
	ds_write_b16_d16_hi v128, v52 offset:2448
	ds_write_b16 v128, v54 offset:2720
	ds_write_b16_d16_hi v128, v54 offset:2992
	ds_write_b16 v128, v56 offset:4352
	ds_write_b16_d16_hi v128, v56 offset:4624
	ds_write_b16 v128, v58 offset:4896
	ds_write_b16_d16_hi v128, v58 offset:5168
	ds_write_b16 v128, v60 offset:6528
	ds_write_b16_d16_hi v128, v60 offset:6800
	ds_write_b16 v128, v62 offset:7072
	ds_write_b16_d16_hi v128, v62 offset:7344
	ds_write_b16 v128, v32 offset:64
	ds_write_b16_d16_hi v128, v32 offset:336
	ds_write_b16 v128, v34 offset:608
	ds_write_b16_d16_hi v128, v34 offset:880
	ds_write_b16 v128, v36 offset:2240
	ds_write_b16_d16_hi v128, v36 offset:2512
	ds_write_b16 v128, v38 offset:2784
	ds_write_b16_d16_hi v128, v38 offset:3056
	ds_write_b16 v128, v40 offset:4416
	ds_write_b16_d16_hi v128, v40 offset:4688
	ds_write_b16 v128, v42 offset:4960
	ds_write_b16_d16_hi v128, v42 offset:5232
	ds_write_b16 v128, v44 offset:6592
	ds_write_b16_d16_hi v128, v44 offset:6864
	ds_write_b16 v128, v46 offset:7136
	ds_write_b16_d16_hi v128, v46 offset:7408
	ds_write_b16 v128, v16 offset:8704
	ds_write_b16_d16_hi v128, v16 offset:8976
	ds_write_b16 v128, v18 offset:9248
	ds_write_b16_d16_hi v128, v18 offset:9520
	ds_write_b16 v128, v20 offset:10880
	ds_write_b16_d16_hi v128, v20 offset:11152
	ds_write_b16 v128, v22 offset:11424
	ds_write_b16_d16_hi v128, v22 offset:11696
	ds_write_b16 v128, v24 offset:13056
	ds_write_b16_d16_hi v128, v24 offset:13328
	ds_write_b16 v128, v26 offset:13600
	ds_write_b16_d16_hi v128, v26 offset:13872
	ds_write_b16 v128, v28 offset:15232
	ds_write_b16_d16_hi v128, v28 offset:15504
	ds_write_b16 v128, v30 offset:15776
	ds_write_b16_d16_hi v128, v30 offset:16048
	ds_write_b16 v128, v0 offset:8768
	ds_write_b16_d16_hi v128, v0 offset:9040
	ds_write_b16 v128, v2 offset:9312
	ds_write_b16_d16_hi v128, v2 offset:9584
	ds_write_b16 v128, v4 offset:10944
	ds_write_b16_d16_hi v128, v4 offset:11216
	ds_write_b16 v128, v6 offset:11488
	ds_write_b16_d16_hi v128, v6 offset:11760
	ds_write_b16 v128, v8 offset:13120
	ds_write_b16_d16_hi v128, v8 offset:13392
	ds_write_b16 v128, v10 offset:13664
	ds_write_b16_d16_hi v128, v10 offset:13936
	ds_write_b16 v128, v12 offset:15296
	ds_write_b16_d16_hi v128, v12 offset:15568
	ds_write_b16 v128, v14 offset:15840
	ds_write_b16_d16_hi v128, v14 offset:16112
	s_waitcnt lgkmcnt(0)
	s_barrier
	ds_read_b128 v[132:135], v129
	ds_read_b128 v[136:139], v129 offset:4352
	ds_read_b128 v[140:143], v129 offset:8704
	ds_read_b128 v[144:147], v129 offset:13056
	ds_read_b128 v[148:151], v129 offset:17408
	ds_read_b128 v[152:155], v129 offset:21760
	ds_read_b128 v[156:159], v129 offset:26112
	ds_read_b128 v[160:163], v129 offset:30464
	v_add_u32_e32 v164, 0x49000, v164
	v_add_u32_e32 v165, 0x49000, v165
	v_add_u32_e32 v166, 0x49000, v166
	v_add_u32_e32 v167, 0x49000, v167
	v_add_u32_e32 v168, 0x49000, v168
	v_add_u32_e32 v169, 0x49000, v169
	v_add_u32_e32 v170, 0x49000, v170
	v_add_u32_e32 v171, 0x49000, v171
	s_and_saveexec_b64 s[46:47], s[42:43]
	s_waitcnt lgkmcnt(7)
	global_store_dwordx4 v164, v[132:135], s[40:41]
	s_waitcnt lgkmcnt(6)
	global_store_dwordx4 v165, v[136:139], s[40:41]
	s_waitcnt lgkmcnt(5)
	global_store_dwordx4 v166, v[140:143], s[40:41]
	s_waitcnt lgkmcnt(4)
	global_store_dwordx4 v167, v[144:147], s[40:41]
	s_waitcnt lgkmcnt(3)
	global_store_dwordx4 v168, v[148:151], s[40:41]
	s_waitcnt lgkmcnt(2)
	global_store_dwordx4 v169, v[152:155], s[40:41]
	s_waitcnt lgkmcnt(1)
	global_store_dwordx4 v170, v[156:159], s[40:41]
	s_waitcnt lgkmcnt(0)
	global_store_dwordx4 v171, v[160:163], s[40:41]
	s_or_b64 exec, exec, s[46:47]
	s_branch .Lmt4_tail_0

.Lv5_c_1:
	ds_write_b128 v189, v[160:163]
	ds_write_b128 v189, v[128:131] offset:4608
	ds_write_b128 v189, v[132:135] offset:9216
	ds_write_b128 v189, v[136:139] offset:13824
	ds_write_b128 v189, v[140:143] offset:18432
	ds_write_b128 v189, v[144:147] offset:23040
	ds_write_b128 v189, v[148:151] offset:27648
	ds_write_b128 v189, v[156:159] offset:32256
	ds_write_b128 v189, v[152:155] offset:36864
	ds_write_b128 v189, v[164:167] offset:41472
	ds_write_b128 v189, v[168:171] offset:46080
	ds_write_b128 v189, v[172:175] offset:50688
	global_load_dwordx4 v[160:163], v190, s[38:39]
	global_load_dwordx4 v[128:131], v191, s[38:39]
	global_load_dwordx4 v[132:135], v192, s[38:39]
	global_load_dwordx4 v[136:139], v193, s[38:39]
	global_load_dwordx4 v[140:143], v194, s[38:39]
	global_load_dwordx4 v[144:147], v195, s[38:39]
	s_waitcnt lgkmcnt(0)
	s_barrier
	ds_read_b128 v[216:219], v188 offset:36864
	ds_read_b128 v[200:203], v187
	ds_read_b128 v[220:223], v188 offset:41472
	ds_read_b128 v[204:207], v187 offset:4608
	ds_read_b128 v[208:211], v187 offset:9216
	ds_read_b128 v[212:215], v176
.LBB0_997:
	s_waitcnt lgkmcnt(4)
	v_mfma_f32_32x32x16_bf16 v[112:127], v[200:203], v[216:219], v[112:127]
	ds_read_b128 v[240:243], v188 offset:36896
	global_load_dwordx4 v[152:155], v190, s[40:41]
	s_waitcnt lgkmcnt(4)
	v_mfma_f32_32x32x16_bf16 v[96:111], v[200:203], v[220:223], v[96:111]
	ds_read_b128 v[224:227], v187 offset:32
	global_load_dwordx4 v[164:167], v191, s[40:41]
	s_waitcnt lgkmcnt(4)
	v_mfma_f32_32x32x16_bf16 v[80:95], v[204:207], v[216:219], v[80:95]
	ds_read_b128 v[244:247], v188 offset:41504
	global_load_dwordx4 v[168:171], v192, s[40:41]
	s_waitcnt lgkmcnt(5)
	v_mfma_f32_32x32x16_bf16 v[64:79], v[204:207], v[220:223], v[64:79]
	ds_read_b128 v[228:231], v187 offset:4640
	global_load_dwordx4 v[172:175], v193, s[40:41]
	s_waitcnt lgkmcnt(5)
	v_mfma_f32_32x32x16_bf16 v[48:63], v[208:211], v[216:219], v[48:63]
	ds_read_b128 v[232:235], v187 offset:9248
	global_load_dwordx4 v[148:151], v196, s[38:39]
	s_waitcnt lgkmcnt(6)
	v_mfma_f32_32x32x16_bf16 v[32:47], v[208:211], v[220:223], v[32:47]
	ds_read_b128 v[236:239], v176 offset:32
	global_load_dwordx4 v[156:159], v197, s[38:39]
	s_add_u32 s38, s38, 0x80
	s_addc_u32 s39, s39, 0
	s_add_u32 s40, s40, 0x80
	s_addc_u32 s41, s41, 0
	s_add_u32 s12, s12, 0x80
	s_waitcnt lgkmcnt(6)
	v_mfma_f32_32x32x16_bf16 v[16:31], v[212:215], v[216:219], v[16:31]
	s_waitcnt lgkmcnt(6)
	v_mfma_f32_32x32x16_bf16 v[0:15], v[212:215], v[220:223], v[0:15]
	s_waitcnt lgkmcnt(4)
	v_mfma_f32_32x32x16_bf16 v[112:127], v[224:227], v[240:243], v[112:127]
	ds_read_b128 v[200:203], v187 offset:64
	s_waitcnt lgkmcnt(4)
	v_mfma_f32_32x32x16_bf16 v[96:111], v[224:227], v[244:247], v[96:111]
	ds_read_b128 v[204:207], v187 offset:4672
	s_waitcnt lgkmcnt(4)
	v_mfma_f32_32x32x16_bf16 v[80:95], v[228:231], v[240:243], v[80:95]
	ds_read_b128 v[208:211], v187 offset:9280
	s_waitcnt lgkmcnt(5)
	v_mfma_f32_32x32x16_bf16 v[64:79], v[228:231], v[244:247], v[64:79]
	ds_read_b128 v[212:215], v176 offset:64
	s_waitcnt lgkmcnt(5)
	v_mfma_f32_32x32x16_bf16 v[48:63], v[232:235], v[240:243], v[48:63]
	ds_read_b128 v[216:219], v188 offset:36928
	s_waitcnt lgkmcnt(6)
	v_mfma_f32_32x32x16_bf16 v[32:47], v[232:235], v[244:247], v[32:47]
	ds_read_b128 v[220:223], v188 offset:41536
	s_waitcnt lgkmcnt(6)
	v_mfma_f32_32x32x16_bf16 v[16:31], v[236:239], v[240:243], v[16:31]
	s_waitcnt lgkmcnt(6)
	v_mfma_f32_32x32x16_bf16 v[0:15], v[236:239], v[244:247], v[0:15]
	s_waitcnt lgkmcnt(1)
	v_mfma_f32_32x32x16_bf16 v[112:127], v[200:203], v[216:219], v[112:127]
	ds_read_b128 v[224:227], v187 offset:96
	s_waitcnt lgkmcnt(1)
	v_mfma_f32_32x32x16_bf16 v[96:111], v[200:203], v[220:223], v[96:111]
	ds_read_b128 v[228:231], v187 offset:4704
	s_waitcnt lgkmcnt(3)
	v_mfma_f32_32x32x16_bf16 v[80:95], v[204:207], v[216:219], v[80:95]
	ds_read_b128 v[232:235], v187 offset:9312
	s_waitcnt lgkmcnt(3)
	v_mfma_f32_32x32x16_bf16 v[64:79], v[204:207], v[220:223], v[64:79]
	ds_read_b128 v[236:239], v176 offset:96
	s_waitcnt lgkmcnt(5)
	v_mfma_f32_32x32x16_bf16 v[48:63], v[208:211], v[216:219], v[48:63]
	ds_read_b128 v[240:243], v188 offset:36960
	s_waitcnt lgkmcnt(5)
	v_mfma_f32_32x32x16_bf16 v[32:47], v[208:211], v[220:223], v[32:47]
	ds_read_b128 v[244:247], v188 offset:41568
	s_waitcnt lgkmcnt(7)
	v_mfma_f32_32x32x16_bf16 v[16:31], v[212:215], v[216:219], v[16:31]
	s_waitcnt lgkmcnt(6)
	v_mfma_f32_32x32x16_bf16 v[0:15], v[212:215], v[220:223], v[0:15]
	s_waitcnt lgkmcnt(0)
	s_barrier
	s_waitcnt vmcnt(6)
	s_waitcnt lgkmcnt(1)
	v_mfma_f32_32x32x16_bf16 v[112:127], v[224:227], v[240:243], v[112:127]
	ds_write_b128 v189, v[160:163]
	ds_write_b128 v189, v[128:131] offset:4608
	s_waitcnt lgkmcnt(2)
	v_mfma_f32_32x32x16_bf16 v[96:111], v[224:227], v[244:247], v[96:111]
	ds_write_b128 v189, v[132:135] offset:9216
	ds_write_b128 v189, v[136:139] offset:13824
	global_load_dwordx4 v[160:163], v190, s[38:39]
	s_waitcnt lgkmcnt(5)
	v_mfma_f32_32x32x16_bf16 v[80:95], v[228:231], v[240:243], v[80:95]
	ds_write_b128 v189, v[140:143] offset:18432
	ds_write_b128 v189, v[144:147] offset:23040
	global_load_dwordx4 v[128:131], v191, s[38:39]
	s_waitcnt lgkmcnt(6)
	v_mfma_f32_32x32x16_bf16 v[64:79], v[228:231], v[244:247], v[64:79]
	s_waitcnt vmcnt(2)
	ds_write_b128 v189, v[148:151] offset:27648
	ds_write_b128 v189, v[156:159] offset:32256
	global_load_dwordx4 v[132:135], v192, s[38:39]
	s_waitcnt lgkmcnt(9)
	v_mfma_f32_32x32x16_bf16 v[48:63], v[232:235], v[240:243], v[48:63]
	ds_write_b128 v189, v[152:155] offset:36864
	ds_write_b128 v189, v[164:167] offset:41472
	global_load_dwordx4 v[136:139], v193, s[38:39]
	s_waitcnt lgkmcnt(10)
	v_mfma_f32_32x32x16_bf16 v[32:47], v[232:235], v[244:247], v[32:47]
	ds_write_b128 v189, v[168:171] offset:46080
	ds_write_b128 v189, v[172:175] offset:50688
	global_load_dwordx4 v[140:143], v194, s[38:39]
	global_load_dwordx4 v[144:147], v195, s[38:39]
	s_waitcnt lgkmcnt(0)
	s_barrier
	ds_read_b128 v[216:219], v188 offset:36864
	ds_read_b128 v[200:203], v187
	ds_read_b128 v[220:223], v188 offset:41472
	ds_read_b128 v[204:207], v187 offset:4608
	ds_read_b128 v[208:211], v187 offset:9216
	ds_read_b128 v[212:215], v176
	s_waitcnt lgkmcnt(15)
	v_mfma_f32_32x32x16_bf16 v[16:31], v[236:239], v[240:243], v[16:31]
	s_waitcnt lgkmcnt(15)
	v_mfma_f32_32x32x16_bf16 v[0:15], v[236:239], v[244:247], v[0:15]
	s_cmpk_lg_i32 s12, 0x780
	s_cbranch_scc1 .LBB0_997
	s_waitcnt lgkmcnt(4)
	v_mfma_f32_32x32x16_bf16 v[112:127], v[200:203], v[216:219], v[112:127]
	ds_read_b128 v[240:243], v188 offset:36896
	s_waitcnt lgkmcnt(4)
	v_mfma_f32_32x32x16_bf16 v[96:111], v[200:203], v[220:223], v[96:111]
	ds_read_b128 v[224:227], v187 offset:32
	s_waitcnt lgkmcnt(4)
	v_mfma_f32_32x32x16_bf16 v[80:95], v[204:207], v[216:219], v[80:95]
	ds_read_b128 v[244:247], v188 offset:41504
	s_waitcnt lgkmcnt(5)
	v_mfma_f32_32x32x16_bf16 v[64:79], v[204:207], v[220:223], v[64:79]
	ds_read_b128 v[228:231], v187 offset:4640
	s_waitcnt lgkmcnt(5)
	v_mfma_f32_32x32x16_bf16 v[48:63], v[208:211], v[216:219], v[48:63]
	ds_read_b128 v[232:235], v187 offset:9248
	s_waitcnt lgkmcnt(6)
	v_mfma_f32_32x32x16_bf16 v[32:47], v[208:211], v[220:223], v[32:47]
	ds_read_b128 v[236:239], v176 offset:32
	s_waitcnt lgkmcnt(6)
	v_mfma_f32_32x32x16_bf16 v[16:31], v[212:215], v[216:219], v[16:31]
	s_waitcnt lgkmcnt(6)
	v_mfma_f32_32x32x16_bf16 v[0:15], v[212:215], v[220:223], v[0:15]
	s_waitcnt lgkmcnt(4)
	v_mfma_f32_32x32x16_bf16 v[112:127], v[224:227], v[240:243], v[112:127]
	ds_read_b128 v[200:203], v187 offset:64
	s_waitcnt lgkmcnt(4)
	v_mfma_f32_32x32x16_bf16 v[96:111], v[224:227], v[244:247], v[96:111]
	ds_read_b128 v[204:207], v187 offset:4672
	s_waitcnt lgkmcnt(4)
	v_mfma_f32_32x32x16_bf16 v[80:95], v[228:231], v[240:243], v[80:95]
	ds_read_b128 v[208:211], v187 offset:9280
	s_waitcnt lgkmcnt(5)
	v_mfma_f32_32x32x16_bf16 v[64:79], v[228:231], v[244:247], v[64:79]
	ds_read_b128 v[212:215], v176 offset:64
	s_waitcnt lgkmcnt(5)
	v_mfma_f32_32x32x16_bf16 v[48:63], v[232:235], v[240:243], v[48:63]
	ds_read_b128 v[216:219], v188 offset:36928
	s_waitcnt lgkmcnt(6)
	v_mfma_f32_32x32x16_bf16 v[32:47], v[232:235], v[244:247], v[32:47]
	ds_read_b128 v[220:223], v188 offset:41536
	s_waitcnt lgkmcnt(6)
	v_mfma_f32_32x32x16_bf16 v[16:31], v[236:239], v[240:243], v[16:31]
	s_waitcnt lgkmcnt(6)
	v_mfma_f32_32x32x16_bf16 v[0:15], v[236:239], v[244:247], v[0:15]
	s_waitcnt lgkmcnt(1)
	v_mfma_f32_32x32x16_bf16 v[112:127], v[200:203], v[216:219], v[112:127]
	ds_read_b128 v[224:227], v187 offset:96
	s_waitcnt lgkmcnt(1)
	v_mfma_f32_32x32x16_bf16 v[96:111], v[200:203], v[220:223], v[96:111]
	ds_read_b128 v[228:231], v187 offset:4704
	s_waitcnt lgkmcnt(3)
	v_mfma_f32_32x32x16_bf16 v[80:95], v[204:207], v[216:219], v[80:95]
	ds_read_b128 v[232:235], v187 offset:9312
	s_waitcnt lgkmcnt(3)
	v_mfma_f32_32x32x16_bf16 v[64:79], v[204:207], v[220:223], v[64:79]
	ds_read_b128 v[236:239], v176 offset:96
	s_waitcnt lgkmcnt(5)
	v_mfma_f32_32x32x16_bf16 v[48:63], v[208:211], v[216:219], v[48:63]
	ds_read_b128 v[240:243], v188 offset:36960
	s_waitcnt lgkmcnt(5)
	v_mfma_f32_32x32x16_bf16 v[32:47], v[208:211], v[220:223], v[32:47]
	ds_read_b128 v[244:247], v188 offset:41568
	s_waitcnt lgkmcnt(7)
	v_mfma_f32_32x32x16_bf16 v[16:31], v[212:215], v[216:219], v[16:31]
	s_waitcnt lgkmcnt(6)
	v_mfma_f32_32x32x16_bf16 v[0:15], v[212:215], v[220:223], v[0:15]
	s_waitcnt lgkmcnt(1)
	v_mfma_f32_32x32x16_bf16 v[112:127], v[224:227], v[240:243], v[112:127]
	s_waitcnt lgkmcnt(0)
	v_mfma_f32_32x32x16_bf16 v[96:111], v[224:227], v[244:247], v[96:111]
	s_waitcnt lgkmcnt(1)
	v_mfma_f32_32x32x16_bf16 v[80:95], v[228:231], v[240:243], v[80:95]
	s_waitcnt lgkmcnt(0)
	v_mfma_f32_32x32x16_bf16 v[64:79], v[228:231], v[244:247], v[64:79]
	s_waitcnt lgkmcnt(1)
	v_mfma_f32_32x32x16_bf16 v[48:63], v[232:235], v[240:243], v[48:63]
	s_waitcnt lgkmcnt(0)
	v_mfma_f32_32x32x16_bf16 v[32:47], v[232:235], v[244:247], v[32:47]
	s_waitcnt lgkmcnt(1)
	v_mfma_f32_32x32x16_bf16 v[16:31], v[236:239], v[240:243], v[16:31]
	s_waitcnt lgkmcnt(0)
	v_mfma_f32_32x32x16_bf16 v[0:15], v[236:239], v[244:247], v[0:15]
	s_waitcnt vmcnt(0)
	s_mul_i32 s42, s6, 0x2000
	s_add_u32 s44, s30, s42
	s_addc_u32 s45, s31, 0
	s_lshl_b32 s42, s58, 1
	s_add_u32 s44, s44, s42
	s_addc_u32 s45, s45, 0
	s_add_u32 s44, s44, 0x7157900
	s_addc_u32 s45, s45, 0
	s_mov_b32 s43, 1
	v_max_f32_e32 v112, 0, v112
	v_max_f32_e32 v113, 0, v113
	v_mul_f32_e32 v112, v112, v112
	v_mul_f32_e32 v113, v113, v113
	v_cvt_pk_bf16_f32 v190, v112, v113
	v_max_f32_e32 v114, 0, v114
	v_max_f32_e32 v115, 0, v115
	v_mul_f32_e32 v114, v114, v114
	v_mul_f32_e32 v115, v115, v115
	v_cvt_pk_bf16_f32 v191, v114, v115
	v_max_f32_e32 v116, 0, v116
	v_max_f32_e32 v117, 0, v117
	v_mul_f32_e32 v116, v116, v116
	v_mul_f32_e32 v117, v117, v117
	v_cvt_pk_bf16_f32 v192, v116, v117
	v_max_f32_e32 v118, 0, v118
	v_max_f32_e32 v119, 0, v119
	v_mul_f32_e32 v118, v118, v118
	v_mul_f32_e32 v119, v119, v119
	v_cvt_pk_bf16_f32 v193, v118, v119
	v_max_f32_e32 v120, 0, v120
	v_max_f32_e32 v121, 0, v121
	v_mul_f32_e32 v120, v120, v120
	v_mul_f32_e32 v121, v121, v121
	v_cvt_pk_bf16_f32 v194, v120, v121
	v_max_f32_e32 v122, 0, v122
	v_max_f32_e32 v123, 0, v123
	v_mul_f32_e32 v122, v122, v122
	v_mul_f32_e32 v123, v123, v123
	v_cvt_pk_bf16_f32 v195, v122, v123
	v_max_f32_e32 v124, 0, v124
	v_max_f32_e32 v125, 0, v125
	v_mul_f32_e32 v124, v124, v124
	v_mul_f32_e32 v125, v125, v125
	v_cvt_pk_bf16_f32 v196, v124, v125
	v_max_f32_e32 v126, 0, v126
	v_max_f32_e32 v127, 0, v127
	v_mul_f32_e32 v126, v126, v126
	v_mul_f32_e32 v127, v127, v127
	v_cvt_pk_bf16_f32 v197, v126, v127
	v_max_f32_e32 v96, 0, v96
	v_max_f32_e32 v97, 0, v97
	v_mul_f32_e32 v96, v96, v96
	v_mul_f32_e32 v97, v97, v97
	v_cvt_pk_bf16_f32 v198, v96, v97
	v_max_f32_e32 v98, 0, v98
	v_max_f32_e32 v99, 0, v99
	v_mul_f32_e32 v98, v98, v98
	v_mul_f32_e32 v99, v99, v99
	v_cvt_pk_bf16_f32 v199, v98, v99
	v_max_f32_e32 v100, 0, v100
	v_max_f32_e32 v101, 0, v101
	v_mul_f32_e32 v100, v100, v100
	v_mul_f32_e32 v101, v101, v101
	v_cvt_pk_bf16_f32 v200, v100, v101
	v_max_f32_e32 v102, 0, v102
	v_max_f32_e32 v103, 0, v103
	v_mul_f32_e32 v102, v102, v102
	v_mul_f32_e32 v103, v103, v103
	v_cvt_pk_bf16_f32 v201, v102, v103
	v_max_f32_e32 v104, 0, v104
	v_max_f32_e32 v105, 0, v105
	v_mul_f32_e32 v104, v104, v104
	v_mul_f32_e32 v105, v105, v105
	v_cvt_pk_bf16_f32 v202, v104, v105
	v_max_f32_e32 v106, 0, v106
	v_max_f32_e32 v107, 0, v107
	v_mul_f32_e32 v106, v106, v106
	v_mul_f32_e32 v107, v107, v107
	v_cvt_pk_bf16_f32 v203, v106, v107
	v_max_f32_e32 v108, 0, v108
	v_max_f32_e32 v109, 0, v109
	v_mul_f32_e32 v108, v108, v108
	v_mul_f32_e32 v109, v109, v109
	v_cvt_pk_bf16_f32 v204, v108, v109
	v_max_f32_e32 v110, 0, v110
	v_max_f32_e32 v111, 0, v111
	v_mul_f32_e32 v110, v110, v110
	v_mul_f32_e32 v111, v111, v111
	v_cvt_pk_bf16_f32 v205, v110, v111
	v_max_f32_e32 v80, 0, v80
	v_max_f32_e32 v81, 0, v81
	v_mul_f32_e32 v80, v80, v80
	v_mul_f32_e32 v81, v81, v81
	v_cvt_pk_bf16_f32 v206, v80, v81
	v_max_f32_e32 v82, 0, v82
	v_max_f32_e32 v83, 0, v83
	v_mul_f32_e32 v82, v82, v82
	v_mul_f32_e32 v83, v83, v83
	v_cvt_pk_bf16_f32 v207, v82, v83
	v_max_f32_e32 v84, 0, v84
	v_max_f32_e32 v85, 0, v85
	v_mul_f32_e32 v84, v84, v84
	v_mul_f32_e32 v85, v85, v85
	v_cvt_pk_bf16_f32 v208, v84, v85
	v_max_f32_e32 v86, 0, v86
	v_max_f32_e32 v87, 0, v87
	v_mul_f32_e32 v86, v86, v86
	v_mul_f32_e32 v87, v87, v87
	v_cvt_pk_bf16_f32 v209, v86, v87
	v_max_f32_e32 v88, 0, v88
	v_max_f32_e32 v89, 0, v89
	v_mul_f32_e32 v88, v88, v88
	v_mul_f32_e32 v89, v89, v89
	v_cvt_pk_bf16_f32 v210, v88, v89
	v_max_f32_e32 v90, 0, v90
	v_max_f32_e32 v91, 0, v91
	v_mul_f32_e32 v90, v90, v90
	v_mul_f32_e32 v91, v91, v91
	v_cvt_pk_bf16_f32 v211, v90, v91
	v_max_f32_e32 v92, 0, v92
	v_max_f32_e32 v93, 0, v93
	v_mul_f32_e32 v92, v92, v92
	v_mul_f32_e32 v93, v93, v93
	v_cvt_pk_bf16_f32 v212, v92, v93
	v_max_f32_e32 v94, 0, v94
	v_max_f32_e32 v95, 0, v95
	v_mul_f32_e32 v94, v94, v94
	v_mul_f32_e32 v95, v95, v95
	v_cvt_pk_bf16_f32 v213, v94, v95
	v_max_f32_e32 v64, 0, v64
	v_max_f32_e32 v65, 0, v65
	v_mul_f32_e32 v64, v64, v64
	v_mul_f32_e32 v65, v65, v65
	v_cvt_pk_bf16_f32 v214, v64, v65
	v_max_f32_e32 v66, 0, v66
	v_max_f32_e32 v67, 0, v67
	v_mul_f32_e32 v66, v66, v66
	v_mul_f32_e32 v67, v67, v67
	v_cvt_pk_bf16_f32 v215, v66, v67
	v_max_f32_e32 v68, 0, v68
	v_max_f32_e32 v69, 0, v69
	v_mul_f32_e32 v68, v68, v68
	v_mul_f32_e32 v69, v69, v69
	v_cvt_pk_bf16_f32 v216, v68, v69
	v_max_f32_e32 v70, 0, v70
	v_max_f32_e32 v71, 0, v71
	v_mul_f32_e32 v70, v70, v70
	v_mul_f32_e32 v71, v71, v71
	v_cvt_pk_bf16_f32 v217, v70, v71
	v_max_f32_e32 v72, 0, v72
	v_max_f32_e32 v73, 0, v73
	v_mul_f32_e32 v72, v72, v72
	v_mul_f32_e32 v73, v73, v73
	v_cvt_pk_bf16_f32 v218, v72, v73
	v_max_f32_e32 v74, 0, v74
	v_max_f32_e32 v75, 0, v75
	v_mul_f32_e32 v74, v74, v74
	v_mul_f32_e32 v75, v75, v75
	v_cvt_pk_bf16_f32 v219, v74, v75
	v_max_f32_e32 v76, 0, v76
	v_max_f32_e32 v77, 0, v77
	v_mul_f32_e32 v76, v76, v76
	v_mul_f32_e32 v77, v77, v77
	v_cvt_pk_bf16_f32 v220, v76, v77
	v_max_f32_e32 v78, 0, v78
	v_max_f32_e32 v79, 0, v79
	v_mul_f32_e32 v78, v78, v78
	v_mul_f32_e32 v79, v79, v79
	v_cvt_pk_bf16_f32 v221, v78, v79
	v_max_f32_e32 v48, 0, v48
	v_max_f32_e32 v49, 0, v49
	v_mul_f32_e32 v48, v48, v48
	v_mul_f32_e32 v49, v49, v49
	v_cvt_pk_bf16_f32 v222, v48, v49
	v_max_f32_e32 v50, 0, v50
	v_max_f32_e32 v51, 0, v51
	v_mul_f32_e32 v50, v50, v50
	v_mul_f32_e32 v51, v51, v51
	v_cvt_pk_bf16_f32 v223, v50, v51
	v_max_f32_e32 v52, 0, v52
	v_max_f32_e32 v53, 0, v53
	v_mul_f32_e32 v52, v52, v52
	v_mul_f32_e32 v53, v53, v53
	v_cvt_pk_bf16_f32 v224, v52, v53
	v_max_f32_e32 v54, 0, v54
	v_max_f32_e32 v55, 0, v55
	v_mul_f32_e32 v54, v54, v54
	v_mul_f32_e32 v55, v55, v55
	v_cvt_pk_bf16_f32 v225, v54, v55
	v_max_f32_e32 v56, 0, v56
	v_max_f32_e32 v57, 0, v57
	v_mul_f32_e32 v56, v56, v56
	v_mul_f32_e32 v57, v57, v57
	v_cvt_pk_bf16_f32 v226, v56, v57
	v_max_f32_e32 v58, 0, v58
	v_max_f32_e32 v59, 0, v59
	v_mul_f32_e32 v58, v58, v58
	v_mul_f32_e32 v59, v59, v59
	v_cvt_pk_bf16_f32 v227, v58, v59
	v_max_f32_e32 v60, 0, v60
	v_max_f32_e32 v61, 0, v61
	v_mul_f32_e32 v60, v60, v60
	v_mul_f32_e32 v61, v61, v61
	v_cvt_pk_bf16_f32 v228, v60, v61
	v_max_f32_e32 v62, 0, v62
	v_max_f32_e32 v63, 0, v63
	v_mul_f32_e32 v62, v62, v62
	v_mul_f32_e32 v63, v63, v63
	v_cvt_pk_bf16_f32 v229, v62, v63
	v_max_f32_e32 v32, 0, v32
	v_max_f32_e32 v33, 0, v33
	v_mul_f32_e32 v32, v32, v32
	v_mul_f32_e32 v33, v33, v33
	v_cvt_pk_bf16_f32 v230, v32, v33
	v_max_f32_e32 v34, 0, v34
	v_max_f32_e32 v35, 0, v35
	v_mul_f32_e32 v34, v34, v34
	v_mul_f32_e32 v35, v35, v35
	v_cvt_pk_bf16_f32 v231, v34, v35
	v_max_f32_e32 v36, 0, v36
	v_max_f32_e32 v37, 0, v37
	v_mul_f32_e32 v36, v36, v36
	v_mul_f32_e32 v37, v37, v37
	v_cvt_pk_bf16_f32 v232, v36, v37
	v_max_f32_e32 v38, 0, v38
	v_max_f32_e32 v39, 0, v39
	v_mul_f32_e32 v38, v38, v38
	v_mul_f32_e32 v39, v39, v39
	v_cvt_pk_bf16_f32 v233, v38, v39
	v_max_f32_e32 v40, 0, v40
	v_max_f32_e32 v41, 0, v41
	v_mul_f32_e32 v40, v40, v40
	v_mul_f32_e32 v41, v41, v41
	v_cvt_pk_bf16_f32 v234, v40, v41
	v_max_f32_e32 v42, 0, v42
	v_max_f32_e32 v43, 0, v43
	v_mul_f32_e32 v42, v42, v42
	v_mul_f32_e32 v43, v43, v43
	v_cvt_pk_bf16_f32 v235, v42, v43
	v_max_f32_e32 v44, 0, v44
	v_max_f32_e32 v45, 0, v45
	v_mul_f32_e32 v44, v44, v44
	v_mul_f32_e32 v45, v45, v45
	v_cvt_pk_bf16_f32 v236, v44, v45
	v_max_f32_e32 v46, 0, v46
	v_max_f32_e32 v47, 0, v47
	v_mul_f32_e32 v46, v46, v46
	v_mul_f32_e32 v47, v47, v47
	v_cvt_pk_bf16_f32 v237, v46, v47
	v_max_f32_e32 v16, 0, v16
	v_max_f32_e32 v17, 0, v17
	v_mul_f32_e32 v16, v16, v16
	v_mul_f32_e32 v17, v17, v17
	v_cvt_pk_bf16_f32 v238, v16, v17
	v_max_f32_e32 v18, 0, v18
	v_max_f32_e32 v19, 0, v19
	v_mul_f32_e32 v18, v18, v18
	v_mul_f32_e32 v19, v19, v19
	v_cvt_pk_bf16_f32 v239, v18, v19
	v_max_f32_e32 v20, 0, v20
	v_max_f32_e32 v21, 0, v21
	v_mul_f32_e32 v20, v20, v20
	v_mul_f32_e32 v21, v21, v21
	v_cvt_pk_bf16_f32 v240, v20, v21
	v_max_f32_e32 v22, 0, v22
	v_max_f32_e32 v23, 0, v23
	v_mul_f32_e32 v22, v22, v22
	v_mul_f32_e32 v23, v23, v23
	v_cvt_pk_bf16_f32 v241, v22, v23
	v_max_f32_e32 v24, 0, v24
	v_max_f32_e32 v25, 0, v25
	v_mul_f32_e32 v24, v24, v24
	v_mul_f32_e32 v25, v25, v25
	v_cvt_pk_bf16_f32 v242, v24, v25
	v_max_f32_e32 v26, 0, v26
	v_max_f32_e32 v27, 0, v27
	v_mul_f32_e32 v26, v26, v26
	v_mul_f32_e32 v27, v27, v27
	v_cvt_pk_bf16_f32 v243, v26, v27
	v_max_f32_e32 v28, 0, v28
	v_max_f32_e32 v29, 0, v29
	v_mul_f32_e32 v28, v28, v28
	v_mul_f32_e32 v29, v29, v29
	v_cvt_pk_bf16_f32 v244, v28, v29
	v_max_f32_e32 v30, 0, v30
	v_max_f32_e32 v31, 0, v31
	v_mul_f32_e32 v30, v30, v30
	v_mul_f32_e32 v31, v31, v31
	v_cvt_pk_bf16_f32 v245, v30, v31
	v_max_f32_e32 v0, 0, v0
	v_max_f32_e32 v1, 0, v1
	v_mul_f32_e32 v0, v0, v0
	v_mul_f32_e32 v1, v1, v1
	v_cvt_pk_bf16_f32 v246, v0, v1
	v_max_f32_e32 v2, 0, v2
	v_max_f32_e32 v3, 0, v3
	v_mul_f32_e32 v2, v2, v2
	v_mul_f32_e32 v3, v3, v3
	v_cvt_pk_bf16_f32 v247, v2, v3
	v_max_f32_e32 v4, 0, v4
	v_max_f32_e32 v5, 0, v5
	v_mul_f32_e32 v4, v4, v4
	v_mul_f32_e32 v5, v5, v5
	v_cvt_pk_bf16_f32 v248, v4, v5
	v_max_f32_e32 v6, 0, v6
	v_max_f32_e32 v7, 0, v7
	v_mul_f32_e32 v6, v6, v6
	v_mul_f32_e32 v7, v7, v7
	v_cvt_pk_bf16_f32 v249, v6, v7
	v_max_f32_e32 v8, 0, v8
	v_max_f32_e32 v9, 0, v9
	v_mul_f32_e32 v8, v8, v8
	v_mul_f32_e32 v9, v9, v9
	v_cvt_pk_bf16_f32 v250, v8, v9
	v_max_f32_e32 v10, 0, v10
	v_max_f32_e32 v11, 0, v11
	v_mul_f32_e32 v10, v10, v10
	v_mul_f32_e32 v11, v11, v11
	v_cvt_pk_bf16_f32 v251, v10, v11
	v_max_f32_e32 v12, 0, v12
	v_max_f32_e32 v13, 0, v13
	v_mul_f32_e32 v12, v12, v12
	v_mul_f32_e32 v13, v13, v13
	v_cvt_pk_bf16_f32 v252, v12, v13
	v_max_f32_e32 v14, 0, v14
	v_max_f32_e32 v15, 0, v15
	v_mul_f32_e32 v14, v14, v14
	v_mul_f32_e32 v15, v15, v15
	v_cvt_pk_bf16_f32 v253, v14, v15
	s_add_i32 s57, s57, s22
	s_add_i32 s56, s56, s22
	s_cmpk_lt_u32 s57, 0x240
	s_cbranch_scc1 .LBB0_996
	v_and_b32_e32 v3, 15, v182
	v_lshrrev_b32_e32 v4, 4, v182
	v_mul_u32_u24_e32 v2, 0x2000, v4
	v_lshl_add_u32 v2, v3, 4, v2
	v_mul_u32_u24_e32 v1, 0x110, v4
	v_lshl_add_u32 v1, v3, 4, v1
	v_lshrrev_b32_e32 v3, 7, v182
	v_bfe_u32 v4, v182, 5, 1
	v_lshlrev_b32_e32 v3, 6, v3
	v_lshl_or_b32 v3, v4, 2, v3
	v_mul_u32_u24_e32 v3, 136, v3
	v_and_b32_e32 v4, 0x5f, v182
	v_add_lshl_u32 v0, v3, v4, 1
	s_barrier
	ds_write_b16 v0, v190
	ds_write_b16_d16_hi v0, v190 offset:272
	ds_write_b16 v0, v191 offset:544
	ds_write_b16_d16_hi v0, v191 offset:816
	ds_write_b16 v0, v192 offset:2176
	ds_write_b16_d16_hi v0, v192 offset:2448
	ds_write_b16 v0, v193 offset:2720
	ds_write_b16_d16_hi v0, v193 offset:2992
	ds_write_b16 v0, v194 offset:4352
	ds_write_b16_d16_hi v0, v194 offset:4624
	ds_write_b16 v0, v195 offset:4896
	ds_write_b16_d16_hi v0, v195 offset:5168
	ds_write_b16 v0, v196 offset:6528
	ds_write_b16_d16_hi v0, v196 offset:6800
	ds_write_b16 v0, v197 offset:7072
	ds_write_b16_d16_hi v0, v197 offset:7344
	ds_write_b16 v0, v198 offset:64
	ds_write_b16_d16_hi v0, v198 offset:336
	ds_write_b16 v0, v199 offset:608
	ds_write_b16_d16_hi v0, v199 offset:880
	ds_write_b16 v0, v200 offset:2240
	ds_write_b16_d16_hi v0, v200 offset:2512
	ds_write_b16 v0, v201 offset:2784
	ds_write_b16_d16_hi v0, v201 offset:3056
	ds_write_b16 v0, v202 offset:4416
	ds_write_b16_d16_hi v0, v202 offset:4688
	ds_write_b16 v0, v203 offset:4960
	ds_write_b16_d16_hi v0, v203 offset:5232
	ds_write_b16 v0, v204 offset:6592
	ds_write_b16_d16_hi v0, v204 offset:6864
	ds_write_b16 v0, v205 offset:7136
	ds_write_b16_d16_hi v0, v205 offset:7408
	ds_write_b16 v0, v206 offset:8704
	ds_write_b16_d16_hi v0, v206 offset:8976
	ds_write_b16 v0, v207 offset:9248
	ds_write_b16_d16_hi v0, v207 offset:9520
	ds_write_b16 v0, v208 offset:10880
	ds_write_b16_d16_hi v0, v208 offset:11152
	ds_write_b16 v0, v209 offset:11424
	ds_write_b16_d16_hi v0, v209 offset:11696
	ds_write_b16 v0, v210 offset:13056
	ds_write_b16_d16_hi v0, v210 offset:13328
	ds_write_b16 v0, v211 offset:13600
	ds_write_b16_d16_hi v0, v211 offset:13872
	ds_write_b16 v0, v212 offset:15232
	ds_write_b16_d16_hi v0, v212 offset:15504
	ds_write_b16 v0, v213 offset:15776
	ds_write_b16_d16_hi v0, v213 offset:16048
	ds_write_b16 v0, v214 offset:8768
	ds_write_b16_d16_hi v0, v214 offset:9040
	ds_write_b16 v0, v215 offset:9312
	ds_write_b16_d16_hi v0, v215 offset:9584
	ds_write_b16 v0, v216 offset:10944
	ds_write_b16_d16_hi v0, v216 offset:11216
	ds_write_b16 v0, v217 offset:11488
	ds_write_b16_d16_hi v0, v217 offset:11760
	ds_write_b16 v0, v218 offset:13120
	ds_write_b16_d16_hi v0, v218 offset:13392
	ds_write_b16 v0, v219 offset:13664
	ds_write_b16_d16_hi v0, v219 offset:13936
	ds_write_b16 v0, v220 offset:15296
	ds_write_b16_d16_hi v0, v220 offset:15568
	ds_write_b16 v0, v221 offset:15840
	ds_write_b16_d16_hi v0, v221 offset:16112
	s_waitcnt lgkmcnt(0)
	s_barrier
	ds_read_b128 v[8:11], v1
	ds_read_b128 v[12:15], v1 offset:4352
	ds_read_b128 v[16:19], v1 offset:8704
	ds_read_b128 v[20:23], v1 offset:13056
	ds_read_b128 v[24:27], v1 offset:17408
	ds_read_b128 v[28:31], v1 offset:21760
	ds_read_b128 v[32:35], v1 offset:26112
	ds_read_b128 v[36:39], v1 offset:30464
	s_add_u32 s38, s44, 0x0
	s_addc_u32 s39, s45, 0
	s_waitcnt lgkmcnt(7)
	global_store_dwordx4 v2, v[8:11], s[38:39]
	s_add_u32 s38, s44, 0x20000
	s_addc_u32 s39, s45, 0
	s_waitcnt lgkmcnt(6)
	global_store_dwordx4 v2, v[12:15], s[38:39]
	s_add_u32 s38, s44, 0x40000
	s_addc_u32 s39, s45, 0
	s_waitcnt lgkmcnt(5)
	global_store_dwordx4 v2, v[16:19], s[38:39]
	s_add_u32 s38, s44, 0x60000
	s_addc_u32 s39, s45, 0
	s_waitcnt lgkmcnt(4)
	global_store_dwordx4 v2, v[20:23], s[38:39]
	s_add_u32 s38, s44, 0x100000
	s_addc_u32 s39, s45, 0
	s_waitcnt lgkmcnt(3)
	global_store_dwordx4 v2, v[24:27], s[38:39]
	s_add_u32 s38, s44, 0x120000
	s_addc_u32 s39, s45, 0
	s_waitcnt lgkmcnt(2)
	global_store_dwordx4 v2, v[28:31], s[38:39]
	s_add_u32 s38, s44, 0x140000
	s_addc_u32 s39, s45, 0
	s_waitcnt lgkmcnt(1)
	global_store_dwordx4 v2, v[32:35], s[38:39]
	s_add_u32 s38, s44, 0x160000
	s_addc_u32 s39, s45, 0
	s_waitcnt lgkmcnt(0)
	global_store_dwordx4 v2, v[36:39], s[38:39]
	s_barrier
	ds_write_b16 v0, v222
	ds_write_b16_d16_hi v0, v222 offset:272
	ds_write_b16 v0, v223 offset:544
	ds_write_b16_d16_hi v0, v223 offset:816
	ds_write_b16 v0, v224 offset:2176
	ds_write_b16_d16_hi v0, v224 offset:2448
	ds_write_b16 v0, v225 offset:2720
	ds_write_b16_d16_hi v0, v225 offset:2992
	ds_write_b16 v0, v226 offset:4352
	ds_write_b16_d16_hi v0, v226 offset:4624
	ds_write_b16 v0, v227 offset:4896
	ds_write_b16_d16_hi v0, v227 offset:5168
	ds_write_b16 v0, v228 offset:6528
	ds_write_b16_d16_hi v0, v228 offset:6800
	ds_write_b16 v0, v229 offset:7072
	ds_write_b16_d16_hi v0, v229 offset:7344
	ds_write_b16 v0, v230 offset:64
	ds_write_b16_d16_hi v0, v230 offset:336
	ds_write_b16 v0, v231 offset:608
	ds_write_b16_d16_hi v0, v231 offset:880
	ds_write_b16 v0, v232 offset:2240
	ds_write_b16_d16_hi v0, v232 offset:2512
	ds_write_b16 v0, v233 offset:2784
	ds_write_b16_d16_hi v0, v233 offset:3056
	ds_write_b16 v0, v234 offset:4416
	ds_write_b16_d16_hi v0, v234 offset:4688
	ds_write_b16 v0, v235 offset:4960
	ds_write_b16_d16_hi v0, v235 offset:5232
	ds_write_b16 v0, v236 offset:6592
	ds_write_b16_d16_hi v0, v236 offset:6864
	ds_write_b16 v0, v237 offset:7136
	ds_write_b16_d16_hi v0, v237 offset:7408
	ds_write_b16 v0, v238 offset:8704
	ds_write_b16_d16_hi v0, v238 offset:8976
	ds_write_b16 v0, v239 offset:9248
	ds_write_b16_d16_hi v0, v239 offset:9520
	ds_write_b16 v0, v240 offset:10880
	ds_write_b16_d16_hi v0, v240 offset:11152
	ds_write_b16 v0, v241 offset:11424
	ds_write_b16_d16_hi v0, v241 offset:11696
	ds_write_b16 v0, v242 offset:13056
	ds_write_b16_d16_hi v0, v242 offset:13328
	ds_write_b16 v0, v243 offset:13600
	ds_write_b16_d16_hi v0, v243 offset:13872
	ds_write_b16 v0, v244 offset:15232
	ds_write_b16_d16_hi v0, v244 offset:15504
	ds_write_b16 v0, v245 offset:15776
	ds_write_b16_d16_hi v0, v245 offset:16048
	ds_write_b16 v0, v246 offset:8768
	ds_write_b16_d16_hi v0, v246 offset:9040
	ds_write_b16 v0, v247 offset:9312
	ds_write_b16_d16_hi v0, v247 offset:9584
	ds_write_b16 v0, v248 offset:10944
	ds_write_b16_d16_hi v0, v248 offset:11216
	ds_write_b16 v0, v249 offset:11488
	ds_write_b16_d16_hi v0, v249 offset:11760
	ds_write_b16 v0, v250 offset:13120
	ds_write_b16_d16_hi v0, v250 offset:13392
	ds_write_b16 v0, v251 offset:13664
	ds_write_b16_d16_hi v0, v251 offset:13936
	ds_write_b16 v0, v252 offset:15296
	ds_write_b16_d16_hi v0, v252 offset:15568
	ds_write_b16 v0, v253 offset:15840
	ds_write_b16_d16_hi v0, v253 offset:16112
	s_waitcnt lgkmcnt(0)
	s_barrier
	ds_read_b128 v[8:11], v1
	ds_read_b128 v[12:15], v1 offset:4352
	ds_read_b128 v[16:19], v1 offset:8704
	ds_read_b128 v[20:23], v1 offset:13056
	ds_read_b128 v[24:27], v1 offset:17408
	ds_read_b128 v[28:31], v1 offset:21760
	ds_read_b128 v[32:35], v1 offset:26112
	ds_read_b128 v[36:39], v1 offset:30464
	s_add_u32 s38, s44, 0x80000
	s_addc_u32 s39, s45, 0
	s_waitcnt lgkmcnt(7)
	global_store_dwordx4 v2, v[8:11], s[38:39]
	s_add_u32 s38, s44, 0xa0000
	s_addc_u32 s39, s45, 0
	s_waitcnt lgkmcnt(6)
	global_store_dwordx4 v2, v[12:15], s[38:39]
	s_add_u32 s38, s44, 0xc0000
	s_addc_u32 s39, s45, 0
	s_waitcnt lgkmcnt(5)
	global_store_dwordx4 v2, v[16:19], s[38:39]
	s_add_u32 s38, s44, 0xe0000
	s_addc_u32 s39, s45, 0
	s_waitcnt lgkmcnt(4)
	global_store_dwordx4 v2, v[20:23], s[38:39]
	s_add_u32 s38, s44, 0x180000
	s_addc_u32 s39, s45, 0
	s_waitcnt lgkmcnt(3)
	global_store_dwordx4 v2, v[24:27], s[38:39]
	s_add_u32 s38, s44, 0x1a0000
	s_addc_u32 s39, s45, 0
	s_waitcnt lgkmcnt(2)
	global_store_dwordx4 v2, v[28:31], s[38:39]
	s_add_u32 s38, s44, 0x1c0000
	s_addc_u32 s39, s45, 0
	s_waitcnt lgkmcnt(1)
	global_store_dwordx4 v2, v[32:35], s[38:39]
	s_add_u32 s38, s44, 0x1e0000
	s_addc_u32 s39, s45, 0
	s_waitcnt lgkmcnt(0)
	global_store_dwordx4 v2, v[36:39], s[38:39]
	s_mov_b32 s43, 0
	s_branch .LBB0_989

.LBB0_1282:
	s_mul_hi_u32 s0, s56, s25
	s_mul_i32 s1, s0, s20
	s_sub_i32 s1, s56, s1
	s_add_i32 s8, s0, 1
	s_sub_i32 s12, s1, s20
	s_cmp_ge_u32 s1, s20
	s_cselect_b32 s0, s8, s0
	s_cselect_b32 s1, s12, s1
	s_add_i32 s8, s0, 1
	s_cmp_ge_u32 s1, s20
	s_cselect_b32 s1, s8, s0
	s_add_i32 s0, s1, s23
	s_mul_i32 s1, s1, s20
	s_sub_i32 s1, s56, s1
	s_add_i32 s1, s1, s19
	s_mul_i32 s8, s0, 0xe38e3900
	v_alignbit_b32 v0, s8, s8, 8
	s_cmp_lt_u32 s1, 8
	v_cmp_gt_u32_e32 vcc, s26, v0
	s_cselect_b64 s[12:13], -1, 0
	s_and_b64 s[12:13], vcc, s[12:13]
	s_and_b64 vcc, exec, s[12:13]
	s_cbranch_vccnz .LBB0_1281
	s_lshl_b32 s12, s0, 8
	s_lshl_b32 s8, s1, 7
	s_mov_b64 s[0:1], s[30:31]
	v_mov_b32_e32 v0, v177
	s_mov_b32 s13, s9
	v_mbcnt_lo_u32_b32 v0, -1, v0
	v_mbcnt_hi_u32_b32 v0, -1, v0
	v_add_u32_e32 v182, s33, v0
	s_lshl_b64 s[16:17], s[12:13], 11
	v_ashrrev_i32_e32 v0, 3, v182
	v_lshlrev_b32_e32 v1, 3, v182
	s_add_u32 s58, s14, s16
	v_and_b32_e32 v6, 56, v1
	v_lshlrev_b32_e32 v1, 11, v0
	s_addc_u32 s59, s15, s17
	v_lshl_or_b32 v176, v6, 1, v1
	v_mul_lo_u32 v7, v0, s21
	v_lshl_add_u64 v[0:1], s[58:59], 0, v[176:177]
	v_add_co_u32_e32 v2, vcc, s27, v0
	s_lshl_b64 s[60:61], s[8:9], 11
	s_nop 0
	v_addc_co_u32_e32 v3, vcc, 0, v1, vcc
	v_add_co_u32_e32 v4, vcc, s34, v0
	s_add_u32 s60, s30, s60
	s_nop 0
	v_addc_co_u32_e32 v5, vcc, 0, v1, vcc
	global_load_dwordx4 v[128:131], v[2:3], off
	global_load_dwordx4 v[132:135], v[4:5], off
	v_add_co_u32_e32 v2, vcc, s35, v0
	s_addc_u32 s61, s31, s61
	s_nop 0
	v_addc_co_u32_e32 v3, vcc, 0, v1, vcc
	v_add_co_u32_e32 v4, vcc, s36, v0
	v_lshl_add_u64 v[178:179], s[60:61], 0, v[176:177]
	s_nop 0
	v_addc_co_u32_e32 v5, vcc, 0, v1, vcc
	global_load_dwordx4 v[136:139], v[2:3], off
	global_load_dwordx4 v[144:147], v[4:5], off
	v_add_co_u32_e32 v2, vcc, s37, v0
	v_bfe_u32 v185, v182, 6, 1
	s_nop 0
	v_addc_co_u32_e32 v3, vcc, 0, v1, vcc
	v_add_co_u32_e32 v4, vcc, s38, v0
	v_and_b32_e32 v184, 31, v182
	s_nop 0
	v_addc_co_u32_e32 v5, vcc, 0, v1, vcc
	v_add_co_u32_e32 v0, vcc, s39, v0
	global_load_dwordx4 v[148:151], v[2:3], off
	global_load_dwordx4 v[152:155], v[4:5], off
	v_addc_co_u32_e32 v1, vcc, 0, v1, vcc
	v_add_co_u32_e32 v2, vcc, s27, v178
	global_load_dwordx4 v[164:167], v176, s[58:59]
	global_load_dwordx4 v[140:143], v176, s[60:61]
	v_addc_co_u32_e32 v3, vcc, 0, v179, vcc
	global_load_dwordx4 v[156:159], v[0:1], off
	global_load_dwordx4 v[160:163], v[2:3], off
	v_add_co_u32_e32 v0, vcc, s34, v178
	v_bfe_u32 v186, v182, 5, 1
	s_nop 0
	v_addc_co_u32_e32 v1, vcc, 0, v179, vcc
	v_add_co_u32_e32 v2, vcc, s35, v178
	s_add_u32 s16, s30, s16
	s_nop 0
	v_addc_co_u32_e32 v3, vcc, 0, v179, vcc
	global_load_dwordx4 v[168:171], v[0:1], off
	global_load_dwordx4 v[172:175], v[2:3], off
	v_and_b32_e32 v0, 0xfffff9f, v182
	v_lshl_or_b32 v2, v185, 6, v184
	v_mul_lo_u32 v3, v0, s40
	v_or_b32_e32 v0, 0x60, v182
	v_lshlrev_b32_e32 v1, 4, v186
	v_mul_lo_u32 v4, v0, s40
	v_mul_u32_u24_e32 v2, 0x90, v2
	s_addc_u32 s17, s31, s17
	v_mov_b32_e32 v0, 0
	v_add_lshl_u32 v189, v7, v6, 1
	v_lshl_add_u64 v[180:181], s[16:17], 0, v[176:177]
	s_mov_b64 s[16:17], 0
	v_add_u32_e32 v188, v1, v3
	v_add_u32_e32 v187, v1, v4
	v_add_u32_e32 v176, v1, v2
	v_mov_b32_e32 v1, v0
	v_mov_b32_e32 v2, v0
	v_mov_b32_e32 v3, v0
	v_mov_b32_e32 v4, v0
	v_mov_b32_e32 v5, v0
	v_mov_b32_e32 v6, v0
	v_mov_b32_e32 v7, v0
	v_mov_b32_e32 v8, v0
	v_mov_b32_e32 v9, v0
	v_mov_b32_e32 v10, v0
	v_mov_b32_e32 v11, v0
	v_mov_b32_e32 v12, v0
	v_mov_b32_e32 v13, v0
	v_mov_b32_e32 v14, v0
	v_mov_b32_e32 v15, v0
	v_mov_b32_e32 v16, v0
	v_mov_b32_e32 v17, v0
	v_mov_b32_e32 v18, v0
	v_mov_b32_e32 v19, v0
	v_mov_b32_e32 v20, v0
	v_mov_b32_e32 v21, v0
	v_mov_b32_e32 v22, v0
	v_mov_b32_e32 v23, v0
	v_mov_b32_e32 v24, v0
	v_mov_b32_e32 v25, v0
	v_mov_b32_e32 v26, v0
	v_mov_b32_e32 v27, v0
	v_mov_b32_e32 v28, v0
	v_mov_b32_e32 v29, v0
	v_mov_b32_e32 v30, v0
	v_mov_b32_e32 v31, v0
	v_mov_b32_e32 v32, v0
	v_mov_b32_e32 v33, v0
	v_mov_b32_e32 v34, v0
	v_mov_b32_e32 v35, v0
	v_mov_b32_e32 v36, v0
	v_mov_b32_e32 v37, v0
	v_mov_b32_e32 v38, v0
	v_mov_b32_e32 v39, v0
	v_mov_b32_e32 v40, v0
	v_mov_b32_e32 v41, v0
	v_mov_b32_e32 v42, v0
	v_mov_b32_e32 v43, v0
	v_mov_b32_e32 v44, v0
	v_mov_b32_e32 v45, v0
	v_mov_b32_e32 v46, v0
	v_mov_b32_e32 v47, v0
	v_mov_b32_e32 v48, v0
	v_mov_b32_e32 v49, v0
	v_mov_b32_e32 v50, v0
	v_mov_b32_e32 v51, v0
	v_mov_b32_e32 v52, v0
	v_mov_b32_e32 v53, v0
	v_mov_b32_e32 v54, v0
	v_mov_b32_e32 v55, v0
	v_mov_b32_e32 v56, v0
	v_mov_b32_e32 v57, v0
	v_mov_b32_e32 v58, v0
	v_mov_b32_e32 v59, v0
	v_mov_b32_e32 v60, v0
	v_mov_b32_e32 v61, v0
	v_mov_b32_e32 v62, v0
	v_mov_b32_e32 v63, v0
	v_mov_b32_e32 v64, v0
	v_mov_b32_e32 v65, v0
	v_mov_b32_e32 v66, v0
	v_mov_b32_e32 v67, v0
	v_mov_b32_e32 v68, v0
	v_mov_b32_e32 v69, v0
	v_mov_b32_e32 v70, v0
	v_mov_b32_e32 v71, v0
	v_mov_b32_e32 v72, v0
	v_mov_b32_e32 v73, v0
	v_mov_b32_e32 v74, v0
	v_mov_b32_e32 v75, v0
	v_mov_b32_e32 v76, v0
	v_mov_b32_e32 v77, v0
	v_mov_b32_e32 v78, v0
	v_mov_b32_e32 v79, v0
	v_mov_b32_e32 v80, v0
	v_mov_b32_e32 v81, v0
	v_mov_b32_e32 v82, v0
	v_mov_b32_e32 v83, v0
	v_mov_b32_e32 v84, v0
	v_mov_b32_e32 v85, v0
	v_mov_b32_e32 v86, v0
	v_mov_b32_e32 v87, v0
	v_mov_b32_e32 v88, v0
	v_mov_b32_e32 v89, v0
	v_mov_b32_e32 v90, v0
	v_mov_b32_e32 v91, v0
	v_mov_b32_e32 v92, v0
	v_mov_b32_e32 v93, v0
	v_mov_b32_e32 v94, v0
	v_mov_b32_e32 v95, v0
	v_mov_b32_e32 v96, v0
	v_mov_b32_e32 v97, v0
	v_mov_b32_e32 v98, v0
	v_mov_b32_e32 v99, v0
	v_mov_b32_e32 v100, v0
	v_mov_b32_e32 v101, v0
	v_mov_b32_e32 v102, v0
	v_mov_b32_e32 v103, v0
	v_mov_b32_e32 v104, v0
	v_mov_b32_e32 v105, v0
	v_mov_b32_e32 v106, v0
	v_mov_b32_e32 v107, v0
	v_mov_b32_e32 v108, v0
	v_mov_b32_e32 v109, v0
	v_mov_b32_e32 v110, v0
	v_mov_b32_e32 v111, v0
	v_mov_b32_e32 v112, v0
	v_mov_b32_e32 v113, v0
	v_mov_b32_e32 v114, v0
	v_mov_b32_e32 v115, v0
	v_mov_b32_e32 v116, v0
	v_mov_b32_e32 v117, v0
	v_mov_b32_e32 v118, v0
	v_mov_b32_e32 v119, v0
	v_mov_b32_e32 v120, v0
	v_mov_b32_e32 v121, v0
	v_mov_b32_e32 v122, v0
	v_mov_b32_e32 v123, v0
	v_mov_b32_e32 v124, v0
	v_mov_b32_e32 v125, v0
	v_mov_b32_e32 v126, v0
	v_mov_b32_e32 v127, v0
	v_readfirstlane_b32 s42, v180
	v_readfirstlane_b32 s43, v181
	v_readfirstlane_b32 s44, v178
	v_readfirstlane_b32 s45, v179
	v_lshrrev_b32_e32 v198, 3, v182
	v_and_b32_e32 v199, 7, v182
	v_lshlrev_b32_e32 v198, 11, v198
	v_lshl_or_b32 v190, v199, 4, v198
	s_lshl_b32 s41, s33, 8
	s_sub_u32 s42, s42, s41
	s_subb_u32 s43, s43, 0
	s_sub_u32 s44, s44, s41
	s_subb_u32 s45, s45, 0
	s_add_u32 s42, s42, 0x2957980
	s_addc_u32 s43, s43, 0
	s_add_u32 s44, s44, 0x80
	s_addc_u32 s45, s45, 0
	v_add_u32_e32 v191, 0x10000, v190
	v_add_u32_e32 v192, 0x20000, v190
	v_add_u32_e32 v193, 0x30000, v190
	v_add_u32_e32 v194, 0x40000, v190
	v_add_u32_e32 v195, 0x50000, v190
	v_add_u32_e32 v196, 0x60000, v190
	v_add_u32_e32 v197, 0x70000, v190
	s_waitcnt lgkmcnt(0)
	s_barrier
	s_waitcnt vmcnt(0)
	ds_write_b128 v189, v[164:167]
	ds_write_b128 v189, v[128:131] offset:4608
	ds_write_b128 v189, v[132:135] offset:9216
	ds_write_b128 v189, v[136:139] offset:13824
	ds_write_b128 v189, v[144:147] offset:18432
	ds_write_b128 v189, v[148:151] offset:23040
	ds_write_b128 v189, v[152:155] offset:27648
	ds_write_b128 v189, v[156:159] offset:32256
	ds_write_b128 v189, v[140:143] offset:36864
	ds_write_b128 v189, v[160:163] offset:41472
	ds_write_b128 v189, v[168:171] offset:46080
	ds_write_b128 v189, v[172:175] offset:50688
	global_load_dwordx4 v[164:167], v190, s[42:43]
	global_load_dwordx4 v[128:131], v191, s[42:43]
	global_load_dwordx4 v[132:135], v192, s[42:43]
	global_load_dwordx4 v[136:139], v193, s[42:43]
	global_load_dwordx4 v[144:147], v194, s[42:43]
	global_load_dwordx4 v[148:151], v195, s[42:43]
	s_waitcnt lgkmcnt(0)
	s_barrier
	ds_read_b128 v[216:219], v176 offset:36864
	ds_read_b128 v[200:203], v188
	ds_read_b128 v[220:223], v176 offset:41472
	ds_read_b128 v[204:207], v188 offset:4608
	ds_read_b128 v[208:211], v188 offset:9216
	ds_read_b128 v[212:215], v187
.LBB0_1284:
	s_waitcnt lgkmcnt(4)
	v_mfma_f32_32x32x16_bf16 v[112:127], v[200:203], v[216:219], v[112:127]
	ds_read_b128 v[240:243], v176 offset:36896
	global_load_dwordx4 v[140:143], v190, s[44:45]
	s_waitcnt lgkmcnt(4)
	v_mfma_f32_32x32x16_bf16 v[96:111], v[200:203], v[220:223], v[96:111]
	ds_read_b128 v[224:227], v188 offset:32
	global_load_dwordx4 v[160:163], v191, s[44:45]
	s_waitcnt lgkmcnt(4)
	v_mfma_f32_32x32x16_bf16 v[80:95], v[204:207], v[216:219], v[80:95]
	ds_read_b128 v[244:247], v176 offset:41504
	global_load_dwordx4 v[168:171], v192, s[44:45]
	s_waitcnt lgkmcnt(5)
	v_mfma_f32_32x32x16_bf16 v[64:79], v[204:207], v[220:223], v[64:79]
	ds_read_b128 v[228:231], v188 offset:4640
	global_load_dwordx4 v[172:175], v193, s[44:45]
	s_waitcnt lgkmcnt(5)
	v_mfma_f32_32x32x16_bf16 v[48:63], v[208:211], v[216:219], v[48:63]
	ds_read_b128 v[232:235], v188 offset:9248
	global_load_dwordx4 v[152:155], v196, s[42:43]
	s_waitcnt lgkmcnt(6)
	v_mfma_f32_32x32x16_bf16 v[32:47], v[208:211], v[220:223], v[32:47]
	ds_read_b128 v[236:239], v187 offset:32
	global_load_dwordx4 v[156:159], v197, s[42:43]
	s_add_u32 s42, s42, 0x80
	s_addc_u32 s43, s43, 0
	s_add_u32 s44, s44, 0x80
	s_addc_u32 s45, s45, 0
	s_add_u32 s16, s16, 0x80
	s_waitcnt lgkmcnt(6)
	v_mfma_f32_32x32x16_bf16 v[16:31], v[212:215], v[216:219], v[16:31]
	s_waitcnt lgkmcnt(6)
	v_mfma_f32_32x32x16_bf16 v[0:15], v[212:215], v[220:223], v[0:15]
	s_waitcnt lgkmcnt(4)
	v_mfma_f32_32x32x16_bf16 v[112:127], v[224:227], v[240:243], v[112:127]
	ds_read_b128 v[200:203], v188 offset:64
	s_waitcnt lgkmcnt(4)
	v_mfma_f32_32x32x16_bf16 v[96:111], v[224:227], v[244:247], v[96:111]
	ds_read_b128 v[204:207], v188 offset:4672
	s_waitcnt lgkmcnt(4)
	v_mfma_f32_32x32x16_bf16 v[80:95], v[228:231], v[240:243], v[80:95]
	ds_read_b128 v[208:211], v188 offset:9280
	s_waitcnt lgkmcnt(5)
	v_mfma_f32_32x32x16_bf16 v[64:79], v[228:231], v[244:247], v[64:79]
	ds_read_b128 v[212:215], v187 offset:64
	s_waitcnt lgkmcnt(5)
	v_mfma_f32_32x32x16_bf16 v[48:63], v[232:235], v[240:243], v[48:63]
	ds_read_b128 v[216:219], v176 offset:36928
	s_waitcnt lgkmcnt(6)
	v_mfma_f32_32x32x16_bf16 v[32:47], v[232:235], v[244:247], v[32:47]
	ds_read_b128 v[220:223], v176 offset:41536
	s_waitcnt lgkmcnt(6)
	v_mfma_f32_32x32x16_bf16 v[16:31], v[236:239], v[240:243], v[16:31]
	s_waitcnt lgkmcnt(6)
	v_mfma_f32_32x32x16_bf16 v[0:15], v[236:239], v[244:247], v[0:15]
	s_waitcnt lgkmcnt(1)
	v_mfma_f32_32x32x16_bf16 v[112:127], v[200:203], v[216:219], v[112:127]
	ds_read_b128 v[224:227], v188 offset:96
	s_waitcnt lgkmcnt(1)
	v_mfma_f32_32x32x16_bf16 v[96:111], v[200:203], v[220:223], v[96:111]
	ds_read_b128 v[228:231], v188 offset:4704
	s_waitcnt lgkmcnt(3)
	v_mfma_f32_32x32x16_bf16 v[80:95], v[204:207], v[216:219], v[80:95]
	ds_read_b128 v[232:235], v188 offset:9312
	s_waitcnt lgkmcnt(3)
	v_mfma_f32_32x32x16_bf16 v[64:79], v[204:207], v[220:223], v[64:79]
	ds_read_b128 v[236:239], v187 offset:96
	s_waitcnt lgkmcnt(5)
	v_mfma_f32_32x32x16_bf16 v[48:63], v[208:211], v[216:219], v[48:63]
	ds_read_b128 v[240:243], v176 offset:36960
	s_waitcnt lgkmcnt(5)
	v_mfma_f32_32x32x16_bf16 v[32:47], v[208:211], v[220:223], v[32:47]
	ds_read_b128 v[244:247], v176 offset:41568
	s_waitcnt lgkmcnt(7)
	v_mfma_f32_32x32x16_bf16 v[16:31], v[212:215], v[216:219], v[16:31]
	s_waitcnt lgkmcnt(6)
	v_mfma_f32_32x32x16_bf16 v[0:15], v[212:215], v[220:223], v[0:15]
	s_waitcnt lgkmcnt(0)
	s_barrier
	s_waitcnt vmcnt(6)
	s_waitcnt lgkmcnt(1)
	v_mfma_f32_32x32x16_bf16 v[112:127], v[224:227], v[240:243], v[112:127]
	ds_write_b128 v189, v[164:167]
	ds_write_b128 v189, v[128:131] offset:4608
	s_waitcnt lgkmcnt(2)
	v_mfma_f32_32x32x16_bf16 v[96:111], v[224:227], v[244:247], v[96:111]
	ds_write_b128 v189, v[132:135] offset:9216
	ds_write_b128 v189, v[136:139] offset:13824
	global_load_dwordx4 v[164:167], v190, s[42:43]
	s_waitcnt lgkmcnt(5)
	v_mfma_f32_32x32x16_bf16 v[80:95], v[228:231], v[240:243], v[80:95]
	ds_write_b128 v189, v[144:147] offset:18432
	ds_write_b128 v189, v[148:151] offset:23040
	global_load_dwordx4 v[128:131], v191, s[42:43]
	s_waitcnt lgkmcnt(6)
	v_mfma_f32_32x32x16_bf16 v[64:79], v[228:231], v[244:247], v[64:79]
	s_waitcnt vmcnt(2)
	ds_write_b128 v189, v[152:155] offset:27648
	ds_write_b128 v189, v[156:159] offset:32256
	global_load_dwordx4 v[132:135], v192, s[42:43]
	s_waitcnt lgkmcnt(9)
	v_mfma_f32_32x32x16_bf16 v[48:63], v[232:235], v[240:243], v[48:63]
	ds_write_b128 v189, v[140:143] offset:36864
	ds_write_b128 v189, v[160:163] offset:41472
	global_load_dwordx4 v[136:139], v193, s[42:43]
	s_waitcnt lgkmcnt(10)
	v_mfma_f32_32x32x16_bf16 v[32:47], v[232:235], v[244:247], v[32:47]
	ds_write_b128 v189, v[168:171] offset:46080
	ds_write_b128 v189, v[172:175] offset:50688
	global_load_dwordx4 v[144:147], v194, s[42:43]
	global_load_dwordx4 v[148:151], v195, s[42:43]
	s_waitcnt lgkmcnt(0)
	s_barrier
	ds_read_b128 v[216:219], v176 offset:36864
	ds_read_b128 v[200:203], v188
	ds_read_b128 v[220:223], v176 offset:41472
	ds_read_b128 v[204:207], v188 offset:4608
	ds_read_b128 v[208:211], v188 offset:9216
	ds_read_b128 v[212:215], v187
	s_waitcnt lgkmcnt(15)
	v_mfma_f32_32x32x16_bf16 v[16:31], v[236:239], v[240:243], v[16:31]
	s_waitcnt lgkmcnt(15)
	v_mfma_f32_32x32x16_bf16 v[0:15], v[236:239], v[244:247], v[0:15]
	s_cmpk_lg_i32 s16, 0x780
	s_cbranch_scc1 .LBB0_1284
	s_waitcnt lgkmcnt(4)
	v_mfma_f32_32x32x16_bf16 v[112:127], v[200:203], v[216:219], v[112:127]
	ds_read_b128 v[240:243], v176 offset:36896
	s_waitcnt lgkmcnt(4)
	v_mfma_f32_32x32x16_bf16 v[96:111], v[200:203], v[220:223], v[96:111]
	ds_read_b128 v[224:227], v188 offset:32
	s_waitcnt lgkmcnt(4)
	v_mfma_f32_32x32x16_bf16 v[80:95], v[204:207], v[216:219], v[80:95]
	ds_read_b128 v[244:247], v176 offset:41504
	s_waitcnt lgkmcnt(5)
	v_mfma_f32_32x32x16_bf16 v[64:79], v[204:207], v[220:223], v[64:79]
	ds_read_b128 v[228:231], v188 offset:4640
	s_waitcnt lgkmcnt(5)
	v_mfma_f32_32x32x16_bf16 v[48:63], v[208:211], v[216:219], v[48:63]
	ds_read_b128 v[232:235], v188 offset:9248
	s_waitcnt lgkmcnt(6)
	v_mfma_f32_32x32x16_bf16 v[32:47], v[208:211], v[220:223], v[32:47]
	ds_read_b128 v[236:239], v187 offset:32
	s_waitcnt lgkmcnt(6)
	v_mfma_f32_32x32x16_bf16 v[16:31], v[212:215], v[216:219], v[16:31]
	s_waitcnt lgkmcnt(6)
	v_mfma_f32_32x32x16_bf16 v[0:15], v[212:215], v[220:223], v[0:15]
	s_waitcnt lgkmcnt(4)
	v_mfma_f32_32x32x16_bf16 v[112:127], v[224:227], v[240:243], v[112:127]
	ds_read_b128 v[200:203], v188 offset:64
	s_waitcnt lgkmcnt(4)
	v_mfma_f32_32x32x16_bf16 v[96:111], v[224:227], v[244:247], v[96:111]
	ds_read_b128 v[204:207], v188 offset:4672
	s_waitcnt lgkmcnt(4)
	v_mfma_f32_32x32x16_bf16 v[80:95], v[228:231], v[240:243], v[80:95]
	ds_read_b128 v[208:211], v188 offset:9280
	s_waitcnt lgkmcnt(5)
	v_mfma_f32_32x32x16_bf16 v[64:79], v[228:231], v[244:247], v[64:79]
	ds_read_b128 v[212:215], v187 offset:64
	s_waitcnt lgkmcnt(5)
	v_mfma_f32_32x32x16_bf16 v[48:63], v[232:235], v[240:243], v[48:63]
	ds_read_b128 v[216:219], v176 offset:36928
	s_waitcnt lgkmcnt(6)
	v_mfma_f32_32x32x16_bf16 v[32:47], v[232:235], v[244:247], v[32:47]
	ds_read_b128 v[220:223], v176 offset:41536
	s_waitcnt lgkmcnt(6)
	v_mfma_f32_32x32x16_bf16 v[16:31], v[236:239], v[240:243], v[16:31]
	s_waitcnt lgkmcnt(6)
	v_mfma_f32_32x32x16_bf16 v[0:15], v[236:239], v[244:247], v[0:15]
	s_waitcnt lgkmcnt(1)
	v_mfma_f32_32x32x16_bf16 v[112:127], v[200:203], v[216:219], v[112:127]
	ds_read_b128 v[224:227], v188 offset:96
	s_waitcnt lgkmcnt(1)
	v_mfma_f32_32x32x16_bf16 v[96:111], v[200:203], v[220:223], v[96:111]
	ds_read_b128 v[228:231], v188 offset:4704
	s_waitcnt lgkmcnt(3)
	v_mfma_f32_32x32x16_bf16 v[80:95], v[204:207], v[216:219], v[80:95]
	ds_read_b128 v[232:235], v188 offset:9312
	s_waitcnt lgkmcnt(3)
	v_mfma_f32_32x32x16_bf16 v[64:79], v[204:207], v[220:223], v[64:79]
	ds_read_b128 v[236:239], v187 offset:96
	s_waitcnt lgkmcnt(5)
	v_mfma_f32_32x32x16_bf16 v[48:63], v[208:211], v[216:219], v[48:63]
	ds_read_b128 v[240:243], v176 offset:36960
	s_waitcnt lgkmcnt(5)
	v_mfma_f32_32x32x16_bf16 v[32:47], v[208:211], v[220:223], v[32:47]
	ds_read_b128 v[244:247], v176 offset:41568
	s_waitcnt lgkmcnt(7)
	v_mfma_f32_32x32x16_bf16 v[16:31], v[212:215], v[216:219], v[16:31]
	s_waitcnt lgkmcnt(6)
	v_mfma_f32_32x32x16_bf16 v[0:15], v[212:215], v[220:223], v[0:15]
	s_waitcnt lgkmcnt(1)
	v_mfma_f32_32x32x16_bf16 v[112:127], v[224:227], v[240:243], v[112:127]
	s_waitcnt lgkmcnt(0)
	v_mfma_f32_32x32x16_bf16 v[96:111], v[224:227], v[244:247], v[96:111]
	s_waitcnt lgkmcnt(1)
	v_mfma_f32_32x32x16_bf16 v[80:95], v[228:231], v[240:243], v[80:95]
	s_waitcnt lgkmcnt(0)
	v_mfma_f32_32x32x16_bf16 v[64:79], v[228:231], v[244:247], v[64:79]
	s_waitcnt lgkmcnt(1)
	v_mfma_f32_32x32x16_bf16 v[48:63], v[232:235], v[240:243], v[48:63]
	s_waitcnt lgkmcnt(0)
	v_mfma_f32_32x32x16_bf16 v[32:47], v[232:235], v[244:247], v[32:47]
	s_waitcnt lgkmcnt(1)
	v_mfma_f32_32x32x16_bf16 v[16:31], v[236:239], v[240:243], v[16:31]
	s_waitcnt lgkmcnt(0)
	v_mfma_f32_32x32x16_bf16 v[0:15], v[236:239], v[244:247], v[0:15]
	s_waitcnt vmcnt(0)
	s_mul_i32 s41, s12, 0x1240
	s_add_u32 s42, s30, s41
	s_addc_u32 s43, s31, 0
	s_lshl_b32 s41, s8, 1
	s_add_u32 s42, s42, s41
	s_addc_u32 s43, s43, 0
	s_add_u32 s42, s42, 0x7157900
	s_addc_u32 s43, s43, 0
	v_and_b32_e32 v131, 15, v182
	v_lshrrev_b32_e32 v172, 4, v182
	v_lshl_add_u32 v130, v131, 3, s8
	s_movk_i32 s41, 0x920
	v_cmp_gt_u32_e64 s[44:45], s41, v130
	v_mul_u32_u24_e32 v164, 0x1240, v172
	v_lshl_add_u32 v164, v131, 4, v164
	v_add_u32_e32 v165, 0x12400, v164
	v_add_u32_e32 v166, 0x24800, v164
	v_add_u32_e32 v167, 0x36c00, v164
	v_add_u32_e32 v168, 0x92000, v164
	v_add_u32_e32 v169, 0xa4400, v164
	v_add_u32_e32 v170, 0xb6800, v164
	v_add_u32_e32 v171, 0xc8c00, v164
	v_mul_u32_u24_e32 v129, 0x110, v172
	v_lshl_add_u32 v129, v131, 4, v129
	v_lshrrev_b32_e32 v131, 7, v182
	v_bfe_u32 v172, v182, 5, 1
	v_lshlrev_b32_e32 v131, 6, v131
	v_lshl_or_b32 v131, v172, 2, v131
	v_mul_u32_u24_e32 v131, 136, v131
	v_and_b32_e32 v172, 0x5f, v182
	v_add_lshl_u32 v128, v131, v172, 1
	s_barrier
	v_cvt_pk_bf16_f32 v112, v112, v113
	v_cvt_pk_bf16_f32 v114, v114, v115
	v_cvt_pk_bf16_f32 v116, v116, v117
	v_cvt_pk_bf16_f32 v118, v118, v119
	v_cvt_pk_bf16_f32 v120, v120, v121
	v_cvt_pk_bf16_f32 v122, v122, v123
	v_cvt_pk_bf16_f32 v124, v124, v125
	v_cvt_pk_bf16_f32 v126, v126, v127
	v_cvt_pk_bf16_f32 v96, v96, v97
	v_cvt_pk_bf16_f32 v98, v98, v99
	v_cvt_pk_bf16_f32 v100, v100, v101
	v_cvt_pk_bf16_f32 v102, v102, v103
	v_cvt_pk_bf16_f32 v104, v104, v105
	v_cvt_pk_bf16_f32 v106, v106, v107
	v_cvt_pk_bf16_f32 v108, v108, v109
	v_cvt_pk_bf16_f32 v110, v110, v111
	v_cvt_pk_bf16_f32 v80, v80, v81
	v_cvt_pk_bf16_f32 v82, v82, v83
	v_cvt_pk_bf16_f32 v84, v84, v85
	v_cvt_pk_bf16_f32 v86, v86, v87
	v_cvt_pk_bf16_f32 v88, v88, v89
	v_cvt_pk_bf16_f32 v90, v90, v91
	v_cvt_pk_bf16_f32 v92, v92, v93
	v_cvt_pk_bf16_f32 v94, v94, v95
	v_cvt_pk_bf16_f32 v64, v64, v65
	v_cvt_pk_bf16_f32 v66, v66, v67
	v_cvt_pk_bf16_f32 v68, v68, v69
	v_cvt_pk_bf16_f32 v70, v70, v71
	v_cvt_pk_bf16_f32 v72, v72, v73
	v_cvt_pk_bf16_f32 v74, v74, v75
	v_cvt_pk_bf16_f32 v76, v76, v77
	v_cvt_pk_bf16_f32 v78, v78, v79
	ds_write_b16 v128, v112
	ds_write_b16_d16_hi v128, v112 offset:272
	ds_write_b16 v128, v114 offset:544
	ds_write_b16_d16_hi v128, v114 offset:816
	ds_write_b16 v128, v116 offset:2176
	ds_write_b16_d16_hi v128, v116 offset:2448
	ds_write_b16 v128, v118 offset:2720
	ds_write_b16_d16_hi v128, v118 offset:2992
	ds_write_b16 v128, v120 offset:4352
	ds_write_b16_d16_hi v128, v120 offset:4624
	ds_write_b16 v128, v122 offset:4896
	ds_write_b16_d16_hi v128, v122 offset:5168
	ds_write_b16 v128, v124 offset:6528
	ds_write_b16_d16_hi v128, v124 offset:6800
	ds_write_b16 v128, v126 offset:7072
	ds_write_b16_d16_hi v128, v126 offset:7344
	ds_write_b16 v128, v96 offset:64
	ds_write_b16_d16_hi v128, v96 offset:336
	ds_write_b16 v128, v98 offset:608
	ds_write_b16_d16_hi v128, v98 offset:880
	ds_write_b16 v128, v100 offset:2240
	ds_write_b16_d16_hi v128, v100 offset:2512
	ds_write_b16 v128, v102 offset:2784
	ds_write_b16_d16_hi v128, v102 offset:3056
	ds_write_b16 v128, v104 offset:4416
	ds_write_b16_d16_hi v128, v104 offset:4688
	ds_write_b16 v128, v106 offset:4960
	ds_write_b16_d16_hi v128, v106 offset:5232
	ds_write_b16 v128, v108 offset:6592
	ds_write_b16_d16_hi v128, v108 offset:6864
	ds_write_b16 v128, v110 offset:7136
	ds_write_b16_d16_hi v128, v110 offset:7408
	ds_write_b16 v128, v80 offset:8704
	ds_write_b16_d16_hi v128, v80 offset:8976
	ds_write_b16 v128, v82 offset:9248
	ds_write_b16_d16_hi v128, v82 offset:9520
	ds_write_b16 v128, v84 offset:10880
	ds_write_b16_d16_hi v128, v84 offset:11152
	ds_write_b16 v128, v86 offset:11424
	ds_write_b16_d16_hi v128, v86 offset:11696
	ds_write_b16 v128, v88 offset:13056
	ds_write_b16_d16_hi v128, v88 offset:13328
	ds_write_b16 v128, v90 offset:13600
	ds_write_b16_d16_hi v128, v90 offset:13872
	ds_write_b16 v128, v92 offset:15232
	ds_write_b16_d16_hi v128, v92 offset:15504
	ds_write_b16 v128, v94 offset:15776
	ds_write_b16_d16_hi v128, v94 offset:16048
	ds_write_b16 v128, v64 offset:8768
	ds_write_b16_d16_hi v128, v64 offset:9040
	ds_write_b16 v128, v66 offset:9312
	ds_write_b16_d16_hi v128, v66 offset:9584
	ds_write_b16 v128, v68 offset:10944
	ds_write_b16_d16_hi v128, v68 offset:11216
	ds_write_b16 v128, v70 offset:11488
	ds_write_b16_d16_hi v128, v70 offset:11760
	ds_write_b16 v128, v72 offset:13120
	ds_write_b16_d16_hi v128, v72 offset:13392
	ds_write_b16 v128, v74 offset:13664
	ds_write_b16_d16_hi v128, v74 offset:13936
	ds_write_b16 v128, v76 offset:15296
	ds_write_b16_d16_hi v128, v76 offset:15568
	ds_write_b16 v128, v78 offset:15840
	ds_write_b16_d16_hi v128, v78 offset:16112
	s_waitcnt lgkmcnt(0)
	s_barrier
	ds_read_b128 v[132:135], v129
	ds_read_b128 v[136:139], v129 offset:4352
	ds_read_b128 v[140:143], v129 offset:8704
	ds_read_b128 v[144:147], v129 offset:13056
	ds_read_b128 v[148:151], v129 offset:17408
	ds_read_b128 v[152:155], v129 offset:21760
	ds_read_b128 v[156:159], v129 offset:26112
	ds_read_b128 v[160:163], v129 offset:30464
	v_cvt_pk_bf16_f32 v48, v48, v49
	v_cvt_pk_bf16_f32 v50, v50, v51
	v_cvt_pk_bf16_f32 v52, v52, v53
	v_cvt_pk_bf16_f32 v54, v54, v55
	v_cvt_pk_bf16_f32 v56, v56, v57
	v_cvt_pk_bf16_f32 v58, v58, v59
	v_cvt_pk_bf16_f32 v60, v60, v61
	v_cvt_pk_bf16_f32 v62, v62, v63
	v_cvt_pk_bf16_f32 v32, v32, v33
	v_cvt_pk_bf16_f32 v34, v34, v35
	v_cvt_pk_bf16_f32 v36, v36, v37
	v_cvt_pk_bf16_f32 v38, v38, v39
	v_cvt_pk_bf16_f32 v40, v40, v41
	v_cvt_pk_bf16_f32 v42, v42, v43
	v_cvt_pk_bf16_f32 v44, v44, v45
	v_cvt_pk_bf16_f32 v46, v46, v47
	v_cvt_pk_bf16_f32 v16, v16, v17
	v_cvt_pk_bf16_f32 v18, v18, v19
	v_cvt_pk_bf16_f32 v20, v20, v21
	v_cvt_pk_bf16_f32 v22, v22, v23
	v_cvt_pk_bf16_f32 v24, v24, v25
	v_cvt_pk_bf16_f32 v26, v26, v27
	v_cvt_pk_bf16_f32 v28, v28, v29
	v_cvt_pk_bf16_f32 v30, v30, v31
	v_cvt_pk_bf16_f32 v0, v0, v1
	v_cvt_pk_bf16_f32 v2, v2, v3
	v_cvt_pk_bf16_f32 v4, v4, v5
	v_cvt_pk_bf16_f32 v6, v6, v7
	v_cvt_pk_bf16_f32 v8, v8, v9
	v_cvt_pk_bf16_f32 v10, v10, v11
	v_cvt_pk_bf16_f32 v12, v12, v13
	v_cvt_pk_bf16_f32 v14, v14, v15
	s_and_saveexec_b64 s[46:47], s[44:45]
	s_waitcnt lgkmcnt(7)
	global_store_dwordx4 v164, v[132:135], s[42:43]
	s_waitcnt lgkmcnt(6)
	global_store_dwordx4 v165, v[136:139], s[42:43]
	s_waitcnt lgkmcnt(5)
	global_store_dwordx4 v166, v[140:143], s[42:43]
	s_waitcnt lgkmcnt(4)
	global_store_dwordx4 v167, v[144:147], s[42:43]
	s_waitcnt lgkmcnt(3)
	global_store_dwordx4 v168, v[148:151], s[42:43]
	s_waitcnt lgkmcnt(2)
	global_store_dwordx4 v169, v[152:155], s[42:43]
	s_waitcnt lgkmcnt(1)
	global_store_dwordx4 v170, v[156:159], s[42:43]
	s_waitcnt lgkmcnt(0)
	global_store_dwordx4 v171, v[160:163], s[42:43]
	s_or_b64 exec, exec, s[46:47]
	s_barrier
	ds_write_b16 v128, v48
	ds_write_b16_d16_hi v128, v48 offset:272
	ds_write_b16 v128, v50 offset:544
	ds_write_b16_d16_hi v128, v50 offset:816
	ds_write_b16 v128, v52 offset:2176
	ds_write_b16_d16_hi v128, v52 offset:2448
	ds_write_b16 v128, v54 offset:2720
	ds_write_b16_d16_hi v128, v54 offset:2992
	ds_write_b16 v128, v56 offset:4352
	ds_write_b16_d16_hi v128, v56 offset:4624
	ds_write_b16 v128, v58 offset:4896
	ds_write_b16_d16_hi v128, v58 offset:5168
	ds_write_b16 v128, v60 offset:6528
	ds_write_b16_d16_hi v128, v60 offset:6800
	ds_write_b16 v128, v62 offset:7072
	ds_write_b16_d16_hi v128, v62 offset:7344
	ds_write_b16 v128, v32 offset:64
	ds_write_b16_d16_hi v128, v32 offset:336
	ds_write_b16 v128, v34 offset:608
	ds_write_b16_d16_hi v128, v34 offset:880
	ds_write_b16 v128, v36 offset:2240
	ds_write_b16_d16_hi v128, v36 offset:2512
	ds_write_b16 v128, v38 offset:2784
	ds_write_b16_d16_hi v128, v38 offset:3056
	ds_write_b16 v128, v40 offset:4416
	ds_write_b16_d16_hi v128, v40 offset:4688
	ds_write_b16 v128, v42 offset:4960
	ds_write_b16_d16_hi v128, v42 offset:5232
	ds_write_b16 v128, v44 offset:6592
	ds_write_b16_d16_hi v128, v44 offset:6864
	ds_write_b16 v128, v46 offset:7136
	ds_write_b16_d16_hi v128, v46 offset:7408
	ds_write_b16 v128, v16 offset:8704
	ds_write_b16_d16_hi v128, v16 offset:8976
	ds_write_b16 v128, v18 offset:9248
	ds_write_b16_d16_hi v128, v18 offset:9520
	ds_write_b16 v128, v20 offset:10880
	ds_write_b16_d16_hi v128, v20 offset:11152
	ds_write_b16 v128, v22 offset:11424
	ds_write_b16_d16_hi v128, v22 offset:11696
	ds_write_b16 v128, v24 offset:13056
	ds_write_b16_d16_hi v128, v24 offset:13328
	ds_write_b16 v128, v26 offset:13600
	ds_write_b16_d16_hi v128, v26 offset:13872
	ds_write_b16 v128, v28 offset:15232
	ds_write_b16_d16_hi v128, v28 offset:15504
	ds_write_b16 v128, v30 offset:15776
	ds_write_b16_d16_hi v128, v30 offset:16048
	ds_write_b16 v128, v0 offset:8768
	ds_write_b16_d16_hi v128, v0 offset:9040
	ds_write_b16 v128, v2 offset:9312
	ds_write_b16_d16_hi v128, v2 offset:9584
	ds_write_b16 v128, v4 offset:10944
	ds_write_b16_d16_hi v128, v4 offset:11216
	ds_write_b16 v128, v6 offset:11488
	ds_write_b16_d16_hi v128, v6 offset:11760
	ds_write_b16 v128, v8 offset:13120
	ds_write_b16_d16_hi v128, v8 offset:13392
	ds_write_b16 v128, v10 offset:13664
	ds_write_b16_d16_hi v128, v10 offset:13936
	ds_write_b16 v128, v12 offset:15296
	ds_write_b16_d16_hi v128, v12 offset:15568
	ds_write_b16 v128, v14 offset:15840
	ds_write_b16_d16_hi v128, v14 offset:16112
	s_waitcnt lgkmcnt(0)
	s_barrier
	ds_read_b128 v[132:135], v129
	ds_read_b128 v[136:139], v129 offset:4352
	ds_read_b128 v[140:143], v129 offset:8704
	ds_read_b128 v[144:147], v129 offset:13056
	ds_read_b128 v[148:151], v129 offset:17408
	ds_read_b128 v[152:155], v129 offset:21760
	ds_read_b128 v[156:159], v129 offset:26112
	ds_read_b128 v[160:163], v129 offset:30464
	v_add_u32_e32 v164, 0x49000, v164
	v_add_u32_e32 v165, 0x49000, v165
	v_add_u32_e32 v166, 0x49000, v166
	v_add_u32_e32 v167, 0x49000, v167
	v_add_u32_e32 v168, 0x49000, v168
	v_add_u32_e32 v169, 0x49000, v169
	v_add_u32_e32 v170, 0x49000, v170
	v_add_u32_e32 v171, 0x49000, v171
	s_and_saveexec_b64 s[46:47], s[44:45]
	s_waitcnt lgkmcnt(7)
	global_store_dwordx4 v164, v[132:135], s[42:43]
	s_waitcnt lgkmcnt(6)
	global_store_dwordx4 v165, v[136:139], s[42:43]
	s_waitcnt lgkmcnt(5)
	global_store_dwordx4 v166, v[140:143], s[42:43]
	s_waitcnt lgkmcnt(4)
	global_store_dwordx4 v167, v[144:147], s[42:43]
	s_waitcnt lgkmcnt(3)
	global_store_dwordx4 v168, v[148:151], s[42:43]
	s_waitcnt lgkmcnt(2)
	global_store_dwordx4 v169, v[152:155], s[42:43]
	s_waitcnt lgkmcnt(1)
	global_store_dwordx4 v170, v[156:159], s[42:43]
	s_waitcnt lgkmcnt(0)
	global_store_dwordx4 v171, v[160:163], s[42:43]
	s_or_b64 exec, exec, s[46:47]
	s_branch .LBB0_1281

.LBB0_1977:
	s_waitcnt lgkmcnt(4)
	v_mfma_f32_32x32x16_bf16 v[112:127], v[200:203], v[216:219], v[112:127]
	ds_read_b128 v[240:243], v188 offset:36896
	global_load_dwordx4 v[152:155], v190, s[40:41]
	s_waitcnt lgkmcnt(4)
	v_mfma_f32_32x32x16_bf16 v[96:111], v[200:203], v[220:223], v[96:111]
	ds_read_b128 v[224:227], v187 offset:32
	global_load_dwordx4 v[164:167], v191, s[40:41]
	s_waitcnt lgkmcnt(4)
	v_mfma_f32_32x32x16_bf16 v[80:95], v[204:207], v[216:219], v[80:95]
	ds_read_b128 v[244:247], v188 offset:41504
	global_load_dwordx4 v[168:171], v192, s[40:41]
	s_waitcnt lgkmcnt(5)
	v_mfma_f32_32x32x16_bf16 v[64:79], v[204:207], v[220:223], v[64:79]
	ds_read_b128 v[228:231], v187 offset:4640
	global_load_dwordx4 v[172:175], v193, s[40:41]
	s_waitcnt lgkmcnt(5)
	v_mfma_f32_32x32x16_bf16 v[48:63], v[208:211], v[216:219], v[48:63]
	ds_read_b128 v[232:235], v187 offset:9248
	global_load_dwordx4 v[148:151], v196, s[38:39]
	s_waitcnt lgkmcnt(6)
	v_mfma_f32_32x32x16_bf16 v[32:47], v[208:211], v[220:223], v[32:47]
	ds_read_b128 v[236:239], v176 offset:32
	global_load_dwordx4 v[156:159], v197, s[38:39]
	s_add_u32 s38, s38, 0x80
	s_addc_u32 s39, s39, 0
	s_add_u32 s40, s40, 0x80
	s_addc_u32 s41, s41, 0
	s_add_u32 s12, s12, 0x80
	s_waitcnt lgkmcnt(6)
	v_mfma_f32_32x32x16_bf16 v[16:31], v[212:215], v[216:219], v[16:31]
	s_waitcnt lgkmcnt(6)
	v_mfma_f32_32x32x16_bf16 v[0:15], v[212:215], v[220:223], v[0:15]
	s_waitcnt lgkmcnt(4)
	v_mfma_f32_32x32x16_bf16 v[112:127], v[224:227], v[240:243], v[112:127]
	ds_read_b128 v[200:203], v187 offset:64
	s_waitcnt lgkmcnt(4)
	v_mfma_f32_32x32x16_bf16 v[96:111], v[224:227], v[244:247], v[96:111]
	ds_read_b128 v[204:207], v187 offset:4672
	s_waitcnt lgkmcnt(4)
	v_mfma_f32_32x32x16_bf16 v[80:95], v[228:231], v[240:243], v[80:95]
	ds_read_b128 v[208:211], v187 offset:9280
	s_waitcnt lgkmcnt(5)
	v_mfma_f32_32x32x16_bf16 v[64:79], v[228:231], v[244:247], v[64:79]
	ds_read_b128 v[212:215], v176 offset:64
	s_waitcnt lgkmcnt(5)
	v_mfma_f32_32x32x16_bf16 v[48:63], v[232:235], v[240:243], v[48:63]
	ds_read_b128 v[216:219], v188 offset:36928
	s_waitcnt lgkmcnt(6)
	v_mfma_f32_32x32x16_bf16 v[32:47], v[232:235], v[244:247], v[32:47]
	ds_read_b128 v[220:223], v188 offset:41536
	s_waitcnt lgkmcnt(6)
	v_mfma_f32_32x32x16_bf16 v[16:31], v[236:239], v[240:243], v[16:31]
	s_waitcnt lgkmcnt(6)
	v_mfma_f32_32x32x16_bf16 v[0:15], v[236:239], v[244:247], v[0:15]
	s_waitcnt lgkmcnt(1)
	v_mfma_f32_32x32x16_bf16 v[112:127], v[200:203], v[216:219], v[112:127]
	ds_read_b128 v[224:227], v187 offset:96
	s_waitcnt lgkmcnt(1)
	v_mfma_f32_32x32x16_bf16 v[96:111], v[200:203], v[220:223], v[96:111]
	ds_read_b128 v[228:231], v187 offset:4704
	s_waitcnt lgkmcnt(3)
	v_mfma_f32_32x32x16_bf16 v[80:95], v[204:207], v[216:219], v[80:95]
	ds_read_b128 v[232:235], v187 offset:9312
	s_waitcnt lgkmcnt(3)
	v_mfma_f32_32x32x16_bf16 v[64:79], v[204:207], v[220:223], v[64:79]
	ds_read_b128 v[236:239], v176 offset:96
	s_waitcnt lgkmcnt(5)
	v_mfma_f32_32x32x16_bf16 v[48:63], v[208:211], v[216:219], v[48:63]
	ds_read_b128 v[240:243], v188 offset:36960
	s_waitcnt lgkmcnt(5)
	v_mfma_f32_32x32x16_bf16 v[32:47], v[208:211], v[220:223], v[32:47]
	ds_read_b128 v[244:247], v188 offset:41568
	s_waitcnt lgkmcnt(7)
	v_mfma_f32_32x32x16_bf16 v[16:31], v[212:215], v[216:219], v[16:31]
	s_waitcnt lgkmcnt(6)
	v_mfma_f32_32x32x16_bf16 v[0:15], v[212:215], v[220:223], v[0:15]
	s_waitcnt lgkmcnt(0)
	s_barrier
	s_waitcnt vmcnt(6)
	s_waitcnt lgkmcnt(1)
	v_mfma_f32_32x32x16_bf16 v[112:127], v[224:227], v[240:243], v[112:127]
	ds_write_b128 v189, v[160:163]
	ds_write_b128 v189, v[128:131] offset:4608
	s_waitcnt lgkmcnt(2)
	v_mfma_f32_32x32x16_bf16 v[96:111], v[224:227], v[244:247], v[96:111]
	ds_write_b128 v189, v[132:135] offset:9216
	ds_write_b128 v189, v[136:139] offset:13824
	global_load_dwordx4 v[160:163], v190, s[38:39]
	s_waitcnt lgkmcnt(5)
	v_mfma_f32_32x32x16_bf16 v[80:95], v[228:231], v[240:243], v[80:95]
	ds_write_b128 v189, v[140:143] offset:18432
	ds_write_b128 v189, v[144:147] offset:23040
	global_load_dwordx4 v[128:131], v191, s[38:39]
	s_waitcnt lgkmcnt(6)
	v_mfma_f32_32x32x16_bf16 v[64:79], v[228:231], v[244:247], v[64:79]
	s_waitcnt vmcnt(2)
	ds_write_b128 v189, v[148:151] offset:27648
	ds_write_b128 v189, v[156:159] offset:32256
	global_load_dwordx4 v[132:135], v192, s[38:39]
	s_waitcnt lgkmcnt(9)
	v_mfma_f32_32x32x16_bf16 v[48:63], v[232:235], v[240:243], v[48:63]
	ds_write_b128 v189, v[152:155] offset:36864
	ds_write_b128 v189, v[164:167] offset:41472
	global_load_dwordx4 v[136:139], v193, s[38:39]
	s_waitcnt lgkmcnt(10)
	v_mfma_f32_32x32x16_bf16 v[32:47], v[232:235], v[244:247], v[32:47]
	ds_write_b128 v189, v[168:171] offset:46080
	ds_write_b128 v189, v[172:175] offset:50688
	global_load_dwordx4 v[140:143], v194, s[38:39]
	global_load_dwordx4 v[144:147], v195, s[38:39]
	s_waitcnt lgkmcnt(0)
	s_barrier
	ds_read_b128 v[216:219], v188 offset:36864
	ds_read_b128 v[200:203], v187
	ds_read_b128 v[220:223], v188 offset:41472
	ds_read_b128 v[204:207], v187 offset:4608
	ds_read_b128 v[208:211], v187 offset:9216
	ds_read_b128 v[212:215], v176
	s_waitcnt lgkmcnt(15)
	v_mfma_f32_32x32x16_bf16 v[16:31], v[236:239], v[240:243], v[16:31]
	s_waitcnt lgkmcnt(15)
	v_mfma_f32_32x32x16_bf16 v[0:15], v[236:239], v[244:247], v[0:15]
	s_cmpk_lg_i32 s12, 0x780
	s_cbranch_scc1 .LBB0_1977
	s_waitcnt lgkmcnt(4)
	v_mfma_f32_32x32x16_bf16 v[112:127], v[200:203], v[216:219], v[112:127]
	ds_read_b128 v[240:243], v188 offset:36896
	s_waitcnt lgkmcnt(4)
	v_mfma_f32_32x32x16_bf16 v[96:111], v[200:203], v[220:223], v[96:111]
	ds_read_b128 v[224:227], v187 offset:32
	s_waitcnt lgkmcnt(4)
	v_mfma_f32_32x32x16_bf16 v[80:95], v[204:207], v[216:219], v[80:95]
	ds_read_b128 v[244:247], v188 offset:41504
	s_waitcnt lgkmcnt(5)
	v_mfma_f32_32x32x16_bf16 v[64:79], v[204:207], v[220:223], v[64:79]
	ds_read_b128 v[228:231], v187 offset:4640
	s_waitcnt lgkmcnt(5)
	v_mfma_f32_32x32x16_bf16 v[48:63], v[208:211], v[216:219], v[48:63]
	ds_read_b128 v[232:235], v187 offset:9248
	s_waitcnt lgkmcnt(6)
	v_mfma_f32_32x32x16_bf16 v[32:47], v[208:211], v[220:223], v[32:47]
	ds_read_b128 v[236:239], v176 offset:32
	s_waitcnt lgkmcnt(6)
	v_mfma_f32_32x32x16_bf16 v[16:31], v[212:215], v[216:219], v[16:31]
	s_waitcnt lgkmcnt(6)
	v_mfma_f32_32x32x16_bf16 v[0:15], v[212:215], v[220:223], v[0:15]
	s_waitcnt lgkmcnt(4)
	v_mfma_f32_32x32x16_bf16 v[112:127], v[224:227], v[240:243], v[112:127]
	ds_read_b128 v[200:203], v187 offset:64
	s_waitcnt lgkmcnt(4)
	v_mfma_f32_32x32x16_bf16 v[96:111], v[224:227], v[244:247], v[96:111]
	ds_read_b128 v[204:207], v187 offset:4672
	s_waitcnt lgkmcnt(4)
	v_mfma_f32_32x32x16_bf16 v[80:95], v[228:231], v[240:243], v[80:95]
	ds_read_b128 v[208:211], v187 offset:9280
	s_waitcnt lgkmcnt(5)
	v_mfma_f32_32x32x16_bf16 v[64:79], v[228:231], v[244:247], v[64:79]
	ds_read_b128 v[212:215], v176 offset:64
	s_waitcnt lgkmcnt(5)
	v_mfma_f32_32x32x16_bf16 v[48:63], v[232:235], v[240:243], v[48:63]
	ds_read_b128 v[216:219], v188 offset:36928
	s_waitcnt lgkmcnt(6)
	v_mfma_f32_32x32x16_bf16 v[32:47], v[232:235], v[244:247], v[32:47]
	ds_read_b128 v[220:223], v188 offset:41536
	s_waitcnt lgkmcnt(6)
	v_mfma_f32_32x32x16_bf16 v[16:31], v[236:239], v[240:243], v[16:31]
	s_waitcnt lgkmcnt(6)
	v_mfma_f32_32x32x16_bf16 v[0:15], v[236:239], v[244:247], v[0:15]
	s_waitcnt lgkmcnt(1)
	v_mfma_f32_32x32x16_bf16 v[112:127], v[200:203], v[216:219], v[112:127]
	ds_read_b128 v[224:227], v187 offset:96
	s_waitcnt lgkmcnt(1)
	v_mfma_f32_32x32x16_bf16 v[96:111], v[200:203], v[220:223], v[96:111]
	ds_read_b128 v[228:231], v187 offset:4704
	s_waitcnt lgkmcnt(3)
	v_mfma_f32_32x32x16_bf16 v[80:95], v[204:207], v[216:219], v[80:95]
	ds_read_b128 v[232:235], v187 offset:9312
	s_waitcnt lgkmcnt(3)
	v_mfma_f32_32x32x16_bf16 v[64:79], v[204:207], v[220:223], v[64:79]
	ds_read_b128 v[236:239], v176 offset:96
	s_waitcnt lgkmcnt(5)
	v_mfma_f32_32x32x16_bf16 v[48:63], v[208:211], v[216:219], v[48:63]
	ds_read_b128 v[240:243], v188 offset:36960
	s_waitcnt lgkmcnt(5)
	v_mfma_f32_32x32x16_bf16 v[32:47], v[208:211], v[220:223], v[32:47]
	ds_read_b128 v[244:247], v188 offset:41568
	s_waitcnt lgkmcnt(7)
	v_mfma_f32_32x32x16_bf16 v[16:31], v[212:215], v[216:219], v[16:31]
	s_waitcnt lgkmcnt(6)
	v_mfma_f32_32x32x16_bf16 v[0:15], v[212:215], v[220:223], v[0:15]
	s_waitcnt lgkmcnt(1)
	v_mfma_f32_32x32x16_bf16 v[112:127], v[224:227], v[240:243], v[112:127]
	s_waitcnt lgkmcnt(0)
	v_mfma_f32_32x32x16_bf16 v[96:111], v[224:227], v[244:247], v[96:111]
	s_waitcnt lgkmcnt(1)
	v_mfma_f32_32x32x16_bf16 v[80:95], v[228:231], v[240:243], v[80:95]
	s_waitcnt lgkmcnt(0)
	v_mfma_f32_32x32x16_bf16 v[64:79], v[228:231], v[244:247], v[64:79]
	s_waitcnt lgkmcnt(1)
	v_mfma_f32_32x32x16_bf16 v[48:63], v[232:235], v[240:243], v[48:63]
	s_waitcnt lgkmcnt(0)
	v_mfma_f32_32x32x16_bf16 v[32:47], v[232:235], v[244:247], v[32:47]
	s_waitcnt lgkmcnt(1)
	v_mfma_f32_32x32x16_bf16 v[16:31], v[236:239], v[240:243], v[16:31]
	s_waitcnt lgkmcnt(0)
	v_mfma_f32_32x32x16_bf16 v[0:15], v[236:239], v[244:247], v[0:15]
	s_waitcnt vmcnt(0)
	s_mul_i32 s42, s6, 0x2000
	s_add_u32 s44, s30, s42
	s_addc_u32 s45, s31, 0
	s_lshl_b32 s42, s58, 1
	s_add_u32 s44, s44, s42
	s_addc_u32 s45, s45, 0
	s_add_u32 s44, s44, 0x7157900
	s_addc_u32 s45, s45, 0
	s_mov_b32 s43, 1
	v_max_f32_e32 v112, 0, v112
	v_max_f32_e32 v113, 0, v113
	v_mul_f32_e32 v112, v112, v112
	v_mul_f32_e32 v113, v113, v113
	v_cvt_pk_bf16_f32 v190, v112, v113
	v_max_f32_e32 v114, 0, v114
	v_max_f32_e32 v115, 0, v115
	v_mul_f32_e32 v114, v114, v114
	v_mul_f32_e32 v115, v115, v115
	v_cvt_pk_bf16_f32 v191, v114, v115
	v_max_f32_e32 v116, 0, v116
	v_max_f32_e32 v117, 0, v117
	v_mul_f32_e32 v116, v116, v116
	v_mul_f32_e32 v117, v117, v117
	v_cvt_pk_bf16_f32 v192, v116, v117
	v_max_f32_e32 v118, 0, v118
	v_max_f32_e32 v119, 0, v119
	v_mul_f32_e32 v118, v118, v118
	v_mul_f32_e32 v119, v119, v119
	v_cvt_pk_bf16_f32 v193, v118, v119
	v_max_f32_e32 v120, 0, v120
	v_max_f32_e32 v121, 0, v121
	v_mul_f32_e32 v120, v120, v120
	v_mul_f32_e32 v121, v121, v121
	v_cvt_pk_bf16_f32 v194, v120, v121
	v_max_f32_e32 v122, 0, v122
	v_max_f32_e32 v123, 0, v123
	v_mul_f32_e32 v122, v122, v122
	v_mul_f32_e32 v123, v123, v123
	v_cvt_pk_bf16_f32 v195, v122, v123
	v_max_f32_e32 v124, 0, v124
	v_max_f32_e32 v125, 0, v125
	v_mul_f32_e32 v124, v124, v124
	v_mul_f32_e32 v125, v125, v125
	v_cvt_pk_bf16_f32 v196, v124, v125
	v_max_f32_e32 v126, 0, v126
	v_max_f32_e32 v127, 0, v127
	v_mul_f32_e32 v126, v126, v126
	v_mul_f32_e32 v127, v127, v127
	v_cvt_pk_bf16_f32 v197, v126, v127
	v_max_f32_e32 v96, 0, v96
	v_max_f32_e32 v97, 0, v97
	v_mul_f32_e32 v96, v96, v96
	v_mul_f32_e32 v97, v97, v97
	v_cvt_pk_bf16_f32 v198, v96, v97
	v_max_f32_e32 v98, 0, v98
	v_max_f32_e32 v99, 0, v99
	v_mul_f32_e32 v98, v98, v98
	v_mul_f32_e32 v99, v99, v99
	v_cvt_pk_bf16_f32 v199, v98, v99
	v_max_f32_e32 v100, 0, v100
	v_max_f32_e32 v101, 0, v101
	v_mul_f32_e32 v100, v100, v100
	v_mul_f32_e32 v101, v101, v101
	v_cvt_pk_bf16_f32 v200, v100, v101
	v_max_f32_e32 v102, 0, v102
	v_max_f32_e32 v103, 0, v103
	v_mul_f32_e32 v102, v102, v102
	v_mul_f32_e32 v103, v103, v103
	v_cvt_pk_bf16_f32 v201, v102, v103
	v_max_f32_e32 v104, 0, v104
	v_max_f32_e32 v105, 0, v105
	v_mul_f32_e32 v104, v104, v104
	v_mul_f32_e32 v105, v105, v105
	v_cvt_pk_bf16_f32 v202, v104, v105
	v_max_f32_e32 v106, 0, v106
	v_max_f32_e32 v107, 0, v107
	v_mul_f32_e32 v106, v106, v106
	v_mul_f32_e32 v107, v107, v107
	v_cvt_pk_bf16_f32 v203, v106, v107
	v_max_f32_e32 v108, 0, v108
	v_max_f32_e32 v109, 0, v109
	v_mul_f32_e32 v108, v108, v108
	v_mul_f32_e32 v109, v109, v109
	v_cvt_pk_bf16_f32 v204, v108, v109
	v_max_f32_e32 v110, 0, v110
	v_max_f32_e32 v111, 0, v111
	v_mul_f32_e32 v110, v110, v110
	v_mul_f32_e32 v111, v111, v111
	v_cvt_pk_bf16_f32 v205, v110, v111
	v_max_f32_e32 v80, 0, v80
	v_max_f32_e32 v81, 0, v81
	v_mul_f32_e32 v80, v80, v80
	v_mul_f32_e32 v81, v81, v81
	v_cvt_pk_bf16_f32 v206, v80, v81
	v_max_f32_e32 v82, 0, v82
	v_max_f32_e32 v83, 0, v83
	v_mul_f32_e32 v82, v82, v82
	v_mul_f32_e32 v83, v83, v83
	v_cvt_pk_bf16_f32 v207, v82, v83
	v_max_f32_e32 v84, 0, v84
	v_max_f32_e32 v85, 0, v85
	v_mul_f32_e32 v84, v84, v84
	v_mul_f32_e32 v85, v85, v85
	v_cvt_pk_bf16_f32 v208, v84, v85
	v_max_f32_e32 v86, 0, v86
	v_max_f32_e32 v87, 0, v87
	v_mul_f32_e32 v86, v86, v86
	v_mul_f32_e32 v87, v87, v87
	v_cvt_pk_bf16_f32 v209, v86, v87
	v_max_f32_e32 v88, 0, v88
	v_max_f32_e32 v89, 0, v89
	v_mul_f32_e32 v88, v88, v88
	v_mul_f32_e32 v89, v89, v89
	v_cvt_pk_bf16_f32 v210, v88, v89
	v_max_f32_e32 v90, 0, v90
	v_max_f32_e32 v91, 0, v91
	v_mul_f32_e32 v90, v90, v90
	v_mul_f32_e32 v91, v91, v91
	v_cvt_pk_bf16_f32 v211, v90, v91
	v_max_f32_e32 v92, 0, v92
	v_max_f32_e32 v93, 0, v93
	v_mul_f32_e32 v92, v92, v92
	v_mul_f32_e32 v93, v93, v93
	v_cvt_pk_bf16_f32 v212, v92, v93
	v_max_f32_e32 v94, 0, v94
	v_max_f32_e32 v95, 0, v95
	v_mul_f32_e32 v94, v94, v94
	v_mul_f32_e32 v95, v95, v95
	v_cvt_pk_bf16_f32 v213, v94, v95
	v_max_f32_e32 v64, 0, v64
	v_max_f32_e32 v65, 0, v65
	v_mul_f32_e32 v64, v64, v64
	v_mul_f32_e32 v65, v65, v65
	v_cvt_pk_bf16_f32 v214, v64, v65
	v_max_f32_e32 v66, 0, v66
	v_max_f32_e32 v67, 0, v67
	v_mul_f32_e32 v66, v66, v66
	v_mul_f32_e32 v67, v67, v67
	v_cvt_pk_bf16_f32 v215, v66, v67
	v_max_f32_e32 v68, 0, v68
	v_max_f32_e32 v69, 0, v69
	v_mul_f32_e32 v68, v68, v68
	v_mul_f32_e32 v69, v69, v69
	v_cvt_pk_bf16_f32 v216, v68, v69
	v_max_f32_e32 v70, 0, v70
	v_max_f32_e32 v71, 0, v71
	v_mul_f32_e32 v70, v70, v70
	v_mul_f32_e32 v71, v71, v71
	v_cvt_pk_bf16_f32 v217, v70, v71
	v_max_f32_e32 v72, 0, v72
	v_max_f32_e32 v73, 0, v73
	v_mul_f32_e32 v72, v72, v72
	v_mul_f32_e32 v73, v73, v73
	v_cvt_pk_bf16_f32 v218, v72, v73
	v_max_f32_e32 v74, 0, v74
	v_max_f32_e32 v75, 0, v75
	v_mul_f32_e32 v74, v74, v74
	v_mul_f32_e32 v75, v75, v75
	v_cvt_pk_bf16_f32 v219, v74, v75
	v_max_f32_e32 v76, 0, v76
	v_max_f32_e32 v77, 0, v77
	v_mul_f32_e32 v76, v76, v76
	v_mul_f32_e32 v77, v77, v77
	v_cvt_pk_bf16_f32 v220, v76, v77
	v_max_f32_e32 v78, 0, v78
	v_max_f32_e32 v79, 0, v79
	v_mul_f32_e32 v78, v78, v78
	v_mul_f32_e32 v79, v79, v79
	v_cvt_pk_bf16_f32 v221, v78, v79
	v_max_f32_e32 v48, 0, v48
	v_max_f32_e32 v49, 0, v49
	v_mul_f32_e32 v48, v48, v48
	v_mul_f32_e32 v49, v49, v49
	v_cvt_pk_bf16_f32 v222, v48, v49
	v_max_f32_e32 v50, 0, v50
	v_max_f32_e32 v51, 0, v51
	v_mul_f32_e32 v50, v50, v50
	v_mul_f32_e32 v51, v51, v51
	v_cvt_pk_bf16_f32 v223, v50, v51
	v_max_f32_e32 v52, 0, v52
	v_max_f32_e32 v53, 0, v53
	v_mul_f32_e32 v52, v52, v52
	v_mul_f32_e32 v53, v53, v53
	v_cvt_pk_bf16_f32 v224, v52, v53
	v_max_f32_e32 v54, 0, v54
	v_max_f32_e32 v55, 0, v55
	v_mul_f32_e32 v54, v54, v54
	v_mul_f32_e32 v55, v55, v55
	v_cvt_pk_bf16_f32 v225, v54, v55
	v_max_f32_e32 v56, 0, v56
	v_max_f32_e32 v57, 0, v57
	v_mul_f32_e32 v56, v56, v56
	v_mul_f32_e32 v57, v57, v57
	v_cvt_pk_bf16_f32 v226, v56, v57
	v_max_f32_e32 v58, 0, v58
	v_max_f32_e32 v59, 0, v59
	v_mul_f32_e32 v58, v58, v58
	v_mul_f32_e32 v59, v59, v59
	v_cvt_pk_bf16_f32 v227, v58, v59
	v_max_f32_e32 v60, 0, v60
	v_max_f32_e32 v61, 0, v61
	v_mul_f32_e32 v60, v60, v60
	v_mul_f32_e32 v61, v61, v61
	v_cvt_pk_bf16_f32 v228, v60, v61
	v_max_f32_e32 v62, 0, v62
	v_max_f32_e32 v63, 0, v63
	v_mul_f32_e32 v62, v62, v62
	v_mul_f32_e32 v63, v63, v63
	v_cvt_pk_bf16_f32 v229, v62, v63
	v_max_f32_e32 v32, 0, v32
	v_max_f32_e32 v33, 0, v33
	v_mul_f32_e32 v32, v32, v32
	v_mul_f32_e32 v33, v33, v33
	v_cvt_pk_bf16_f32 v230, v32, v33
	v_max_f32_e32 v34, 0, v34
	v_max_f32_e32 v35, 0, v35
	v_mul_f32_e32 v34, v34, v34
	v_mul_f32_e32 v35, v35, v35
	v_cvt_pk_bf16_f32 v231, v34, v35
	v_max_f32_e32 v36, 0, v36
	v_max_f32_e32 v37, 0, v37
	v_mul_f32_e32 v36, v36, v36
	v_mul_f32_e32 v37, v37, v37
	v_cvt_pk_bf16_f32 v232, v36, v37
	v_max_f32_e32 v38, 0, v38
	v_max_f32_e32 v39, 0, v39
	v_mul_f32_e32 v38, v38, v38
	v_mul_f32_e32 v39, v39, v39
	v_cvt_pk_bf16_f32 v233, v38, v39
	v_max_f32_e32 v40, 0, v40
	v_max_f32_e32 v41, 0, v41
	v_mul_f32_e32 v40, v40, v40
	v_mul_f32_e32 v41, v41, v41
	v_cvt_pk_bf16_f32 v234, v40, v41
	v_max_f32_e32 v42, 0, v42
	v_max_f32_e32 v43, 0, v43
	v_mul_f32_e32 v42, v42, v42
	v_mul_f32_e32 v43, v43, v43
	v_cvt_pk_bf16_f32 v235, v42, v43
	v_max_f32_e32 v44, 0, v44
	v_max_f32_e32 v45, 0, v45
	v_mul_f32_e32 v44, v44, v44
	v_mul_f32_e32 v45, v45, v45
	v_cvt_pk_bf16_f32 v236, v44, v45
	v_max_f32_e32 v46, 0, v46
	v_max_f32_e32 v47, 0, v47
	v_mul_f32_e32 v46, v46, v46
	v_mul_f32_e32 v47, v47, v47
	v_cvt_pk_bf16_f32 v237, v46, v47
	v_max_f32_e32 v16, 0, v16
	v_max_f32_e32 v17, 0, v17
	v_mul_f32_e32 v16, v16, v16
	v_mul_f32_e32 v17, v17, v17
	v_cvt_pk_bf16_f32 v238, v16, v17
	v_max_f32_e32 v18, 0, v18
	v_max_f32_e32 v19, 0, v19
	v_mul_f32_e32 v18, v18, v18
	v_mul_f32_e32 v19, v19, v19
	v_cvt_pk_bf16_f32 v239, v18, v19
	v_max_f32_e32 v20, 0, v20
	v_max_f32_e32 v21, 0, v21
	v_mul_f32_e32 v20, v20, v20
	v_mul_f32_e32 v21, v21, v21
	v_cvt_pk_bf16_f32 v240, v20, v21
	v_max_f32_e32 v22, 0, v22
	v_max_f32_e32 v23, 0, v23
	v_mul_f32_e32 v22, v22, v22
	v_mul_f32_e32 v23, v23, v23
	v_cvt_pk_bf16_f32 v241, v22, v23
	v_max_f32_e32 v24, 0, v24
	v_max_f32_e32 v25, 0, v25
	v_mul_f32_e32 v24, v24, v24
	v_mul_f32_e32 v25, v25, v25
	v_cvt_pk_bf16_f32 v242, v24, v25
	v_max_f32_e32 v26, 0, v26
	v_max_f32_e32 v27, 0, v27
	v_mul_f32_e32 v26, v26, v26
	v_mul_f32_e32 v27, v27, v27
	v_cvt_pk_bf16_f32 v243, v26, v27
	v_max_f32_e32 v28, 0, v28
	v_max_f32_e32 v29, 0, v29
	v_mul_f32_e32 v28, v28, v28
	v_mul_f32_e32 v29, v29, v29
	v_cvt_pk_bf16_f32 v244, v28, v29
	v_max_f32_e32 v30, 0, v30
	v_max_f32_e32 v31, 0, v31
	v_mul_f32_e32 v30, v30, v30
	v_mul_f32_e32 v31, v31, v31
	v_cvt_pk_bf16_f32 v245, v30, v31
	v_max_f32_e32 v0, 0, v0
	v_max_f32_e32 v1, 0, v1
	v_mul_f32_e32 v0, v0, v0
	v_mul_f32_e32 v1, v1, v1
	v_cvt_pk_bf16_f32 v246, v0, v1
	v_max_f32_e32 v2, 0, v2
	v_max_f32_e32 v3, 0, v3
	v_mul_f32_e32 v2, v2, v2
	v_mul_f32_e32 v3, v3, v3
	v_cvt_pk_bf16_f32 v247, v2, v3
	v_max_f32_e32 v4, 0, v4
	v_max_f32_e32 v5, 0, v5
	v_mul_f32_e32 v4, v4, v4
	v_mul_f32_e32 v5, v5, v5
	v_cvt_pk_bf16_f32 v248, v4, v5
	v_max_f32_e32 v6, 0, v6
	v_max_f32_e32 v7, 0, v7
	v_mul_f32_e32 v6, v6, v6
	v_mul_f32_e32 v7, v7, v7
	v_cvt_pk_bf16_f32 v249, v6, v7
	v_max_f32_e32 v8, 0, v8
	v_max_f32_e32 v9, 0, v9
	v_mul_f32_e32 v8, v8, v8
	v_mul_f32_e32 v9, v9, v9
	v_cvt_pk_bf16_f32 v250, v8, v9
	v_max_f32_e32 v10, 0, v10
	v_max_f32_e32 v11, 0, v11
	v_mul_f32_e32 v10, v10, v10
	v_mul_f32_e32 v11, v11, v11
	v_cvt_pk_bf16_f32 v251, v10, v11
	v_max_f32_e32 v12, 0, v12
	v_max_f32_e32 v13, 0, v13
	v_mul_f32_e32 v12, v12, v12
	v_mul_f32_e32 v13, v13, v13
	v_cvt_pk_bf16_f32 v252, v12, v13
	v_max_f32_e32 v14, 0, v14
	v_max_f32_e32 v15, 0, v15
	v_mul_f32_e32 v14, v14, v14
	v_mul_f32_e32 v15, v15, v15
	v_cvt_pk_bf16_f32 v253, v14, v15
	s_add_i32 s57, s57, s21
	s_add_i32 s56, s56, s21
	s_cmpk_lt_u32 s57, 0x200
	s_cbranch_scc1 .LBB0_1976
	v_and_b32_e32 v3, 15, v182
	v_lshrrev_b32_e32 v4, 4, v182
	v_mul_u32_u24_e32 v2, 0x2000, v4
	v_lshl_add_u32 v2, v3, 4, v2
	v_mul_u32_u24_e32 v1, 0x110, v4
	v_lshl_add_u32 v1, v3, 4, v1
	v_lshrrev_b32_e32 v3, 7, v182
	v_bfe_u32 v4, v182, 5, 1
	v_lshlrev_b32_e32 v3, 6, v3
	v_lshl_or_b32 v3, v4, 2, v3
	v_mul_u32_u24_e32 v3, 136, v3
	v_and_b32_e32 v4, 0x5f, v182
	v_add_lshl_u32 v0, v3, v4, 1
	s_barrier
	ds_write_b16 v0, v190
	ds_write_b16_d16_hi v0, v190 offset:272
	ds_write_b16 v0, v191 offset:544
	ds_write_b16_d16_hi v0, v191 offset:816
	ds_write_b16 v0, v192 offset:2176
	ds_write_b16_d16_hi v0, v192 offset:2448
	ds_write_b16 v0, v193 offset:2720
	ds_write_b16_d16_hi v0, v193 offset:2992
	ds_write_b16 v0, v194 offset:4352
	ds_write_b16_d16_hi v0, v194 offset:4624
	ds_write_b16 v0, v195 offset:4896
	ds_write_b16_d16_hi v0, v195 offset:5168
	ds_write_b16 v0, v196 offset:6528
	ds_write_b16_d16_hi v0, v196 offset:6800
	ds_write_b16 v0, v197 offset:7072
	ds_write_b16_d16_hi v0, v197 offset:7344
	ds_write_b16 v0, v198 offset:64
	ds_write_b16_d16_hi v0, v198 offset:336
	ds_write_b16 v0, v199 offset:608
	ds_write_b16_d16_hi v0, v199 offset:880
	ds_write_b16 v0, v200 offset:2240
	ds_write_b16_d16_hi v0, v200 offset:2512
	ds_write_b16 v0, v201 offset:2784
	ds_write_b16_d16_hi v0, v201 offset:3056
	ds_write_b16 v0, v202 offset:4416
	ds_write_b16_d16_hi v0, v202 offset:4688
	ds_write_b16 v0, v203 offset:4960
	ds_write_b16_d16_hi v0, v203 offset:5232
	ds_write_b16 v0, v204 offset:6592
	ds_write_b16_d16_hi v0, v204 offset:6864
	ds_write_b16 v0, v205 offset:7136
	ds_write_b16_d16_hi v0, v205 offset:7408
	ds_write_b16 v0, v206 offset:8704
	ds_write_b16_d16_hi v0, v206 offset:8976
	ds_write_b16 v0, v207 offset:9248
	ds_write_b16_d16_hi v0, v207 offset:9520
	ds_write_b16 v0, v208 offset:10880
	ds_write_b16_d16_hi v0, v208 offset:11152
	ds_write_b16 v0, v209 offset:11424
	ds_write_b16_d16_hi v0, v209 offset:11696
	ds_write_b16 v0, v210 offset:13056
	ds_write_b16_d16_hi v0, v210 offset:13328
	ds_write_b16 v0, v211 offset:13600
	ds_write_b16_d16_hi v0, v211 offset:13872
	ds_write_b16 v0, v212 offset:15232
	ds_write_b16_d16_hi v0, v212 offset:15504
	ds_write_b16 v0, v213 offset:15776
	ds_write_b16_d16_hi v0, v213 offset:16048
	ds_write_b16 v0, v214 offset:8768
	ds_write_b16_d16_hi v0, v214 offset:9040
	ds_write_b16 v0, v215 offset:9312
	ds_write_b16_d16_hi v0, v215 offset:9584
	ds_write_b16 v0, v216 offset:10944
	ds_write_b16_d16_hi v0, v216 offset:11216
	ds_write_b16 v0, v217 offset:11488
	ds_write_b16_d16_hi v0, v217 offset:11760
	ds_write_b16 v0, v218 offset:13120
	ds_write_b16_d16_hi v0, v218 offset:13392
	ds_write_b16 v0, v219 offset:13664
	ds_write_b16_d16_hi v0, v219 offset:13936
	ds_write_b16 v0, v220 offset:15296
	ds_write_b16_d16_hi v0, v220 offset:15568
	ds_write_b16 v0, v221 offset:15840
	ds_write_b16_d16_hi v0, v221 offset:16112
	s_waitcnt lgkmcnt(0)
	s_barrier
	ds_read_b128 v[8:11], v1
	ds_read_b128 v[12:15], v1 offset:4352
	ds_read_b128 v[16:19], v1 offset:8704
	ds_read_b128 v[20:23], v1 offset:13056
	ds_read_b128 v[24:27], v1 offset:17408
	ds_read_b128 v[28:31], v1 offset:21760
	ds_read_b128 v[32:35], v1 offset:26112
	ds_read_b128 v[36:39], v1 offset:30464
	s_add_u32 s38, s44, 0x0
	s_addc_u32 s39, s45, 0
	s_waitcnt lgkmcnt(7)
	global_store_dwordx4 v2, v[8:11], s[38:39]
	s_add_u32 s38, s44, 0x20000
	s_addc_u32 s39, s45, 0
	s_waitcnt lgkmcnt(6)
	global_store_dwordx4 v2, v[12:15], s[38:39]
	s_add_u32 s38, s44, 0x40000
	s_addc_u32 s39, s45, 0
	s_waitcnt lgkmcnt(5)
	global_store_dwordx4 v2, v[16:19], s[38:39]
	s_add_u32 s38, s44, 0x60000
	s_addc_u32 s39, s45, 0
	s_waitcnt lgkmcnt(4)
	global_store_dwordx4 v2, v[20:23], s[38:39]
	s_add_u32 s38, s44, 0x100000
	s_addc_u32 s39, s45, 0
	s_waitcnt lgkmcnt(3)
	global_store_dwordx4 v2, v[24:27], s[38:39]
	s_add_u32 s38, s44, 0x120000
	s_addc_u32 s39, s45, 0
	s_waitcnt lgkmcnt(2)
	global_store_dwordx4 v2, v[28:31], s[38:39]
	s_add_u32 s38, s44, 0x140000
	s_addc_u32 s39, s45, 0
	s_waitcnt lgkmcnt(1)
	global_store_dwordx4 v2, v[32:35], s[38:39]
	s_add_u32 s38, s44, 0x160000
	s_addc_u32 s39, s45, 0
	s_waitcnt lgkmcnt(0)
	global_store_dwordx4 v2, v[36:39], s[38:39]
	s_barrier
	ds_write_b16 v0, v222
	ds_write_b16_d16_hi v0, v222 offset:272
	ds_write_b16 v0, v223 offset:544
	ds_write_b16_d16_hi v0, v223 offset:816
	ds_write_b16 v0, v224 offset:2176
	ds_write_b16_d16_hi v0, v224 offset:2448
	ds_write_b16 v0, v225 offset:2720
	ds_write_b16_d16_hi v0, v225 offset:2992
	ds_write_b16 v0, v226 offset:4352
	ds_write_b16_d16_hi v0, v226 offset:4624
	ds_write_b16 v0, v227 offset:4896
	ds_write_b16_d16_hi v0, v227 offset:5168
	ds_write_b16 v0, v228 offset:6528
	ds_write_b16_d16_hi v0, v228 offset:6800
	ds_write_b16 v0, v229 offset:7072
	ds_write_b16_d16_hi v0, v229 offset:7344
	ds_write_b16 v0, v230 offset:64
	ds_write_b16_d16_hi v0, v230 offset:336
	ds_write_b16 v0, v231 offset:608
	ds_write_b16_d16_hi v0, v231 offset:880
	ds_write_b16 v0, v232 offset:2240
	ds_write_b16_d16_hi v0, v232 offset:2512
	ds_write_b16 v0, v233 offset:2784
	ds_write_b16_d16_hi v0, v233 offset:3056
	ds_write_b16 v0, v234 offset:4416
	ds_write_b16_d16_hi v0, v234 offset:4688
	ds_write_b16 v0, v235 offset:4960
	ds_write_b16_d16_hi v0, v235 offset:5232
	ds_write_b16 v0, v236 offset:6592
	ds_write_b16_d16_hi v0, v236 offset:6864
	ds_write_b16 v0, v237 offset:7136
	ds_write_b16_d16_hi v0, v237 offset:7408
	ds_write_b16 v0, v238 offset:8704
	ds_write_b16_d16_hi v0, v238 offset:8976
	ds_write_b16 v0, v239 offset:9248
	ds_write_b16_d16_hi v0, v239 offset:9520
	ds_write_b16 v0, v240 offset:10880
	ds_write_b16_d16_hi v0, v240 offset:11152
	ds_write_b16 v0, v241 offset:11424
	ds_write_b16_d16_hi v0, v241 offset:11696
	ds_write_b16 v0, v242 offset:13056
	ds_write_b16_d16_hi v0, v242 offset:13328
	ds_write_b16 v0, v243 offset:13600
	ds_write_b16_d16_hi v0, v243 offset:13872
	ds_write_b16 v0, v244 offset:15232
	ds_write_b16_d16_hi v0, v244 offset:15504
	ds_write_b16 v0, v245 offset:15776
	ds_write_b16_d16_hi v0, v245 offset:16048
	ds_write_b16 v0, v246 offset:8768
	ds_write_b16_d16_hi v0, v246 offset:9040
	ds_write_b16 v0, v247 offset:9312
	ds_write_b16_d16_hi v0, v247 offset:9584
	ds_write_b16 v0, v248 offset:10944
	ds_write_b16_d16_hi v0, v248 offset:11216
	ds_write_b16 v0, v249 offset:11488
	ds_write_b16_d16_hi v0, v249 offset:11760
	ds_write_b16 v0, v250 offset:13120
	ds_write_b16_d16_hi v0, v250 offset:13392
	ds_write_b16 v0, v251 offset:13664
	ds_write_b16_d16_hi v0, v251 offset:13936
	ds_write_b16 v0, v252 offset:15296
	ds_write_b16_d16_hi v0, v252 offset:15568
	ds_write_b16 v0, v253 offset:15840
	ds_write_b16_d16_hi v0, v253 offset:16112
	s_waitcnt lgkmcnt(0)
	s_barrier
	ds_read_b128 v[8:11], v1
	ds_read_b128 v[12:15], v1 offset:4352
	ds_read_b128 v[16:19], v1 offset:8704
	ds_read_b128 v[20:23], v1 offset:13056
	ds_read_b128 v[24:27], v1 offset:17408
	ds_read_b128 v[28:31], v1 offset:21760
	ds_read_b128 v[32:35], v1 offset:26112
	ds_read_b128 v[36:39], v1 offset:30464
	s_add_u32 s38, s44, 0x80000
	s_addc_u32 s39, s45, 0
	s_waitcnt lgkmcnt(7)
	global_store_dwordx4 v2, v[8:11], s[38:39]
	s_add_u32 s38, s44, 0xa0000
	s_addc_u32 s39, s45, 0
	s_waitcnt lgkmcnt(6)
	global_store_dwordx4 v2, v[12:15], s[38:39]
	s_add_u32 s38, s44, 0xc0000
	s_addc_u32 s39, s45, 0
	s_waitcnt lgkmcnt(5)
	global_store_dwordx4 v2, v[16:19], s[38:39]
	s_add_u32 s38, s44, 0xe0000
	s_addc_u32 s39, s45, 0
	s_waitcnt lgkmcnt(4)
	global_store_dwordx4 v2, v[20:23], s[38:39]
	s_add_u32 s38, s44, 0x180000
	s_addc_u32 s39, s45, 0
	s_waitcnt lgkmcnt(3)
	global_store_dwordx4 v2, v[24:27], s[38:39]
	s_add_u32 s38, s44, 0x1a0000
	s_addc_u32 s39, s45, 0
	s_waitcnt lgkmcnt(2)
	global_store_dwordx4 v2, v[28:31], s[38:39]
	s_add_u32 s38, s44, 0x1c0000
	s_addc_u32 s39, s45, 0
	s_waitcnt lgkmcnt(1)
	global_store_dwordx4 v2, v[32:35], s[38:39]
	s_add_u32 s38, s44, 0x1e0000
	s_addc_u32 s39, s45, 0
	s_waitcnt lgkmcnt(0)
	global_store_dwordx4 v2, v[36:39], s[38:39]
	s_mov_b32 s43, 0
	s_branch .LBB0_1969
